# GEMM K-loops: loop counter/pointer SALU and exit compare hoisted above the loop-back barrier (loop-edge edit)
# baseline (speedup 1.0000x reference)
; #define PG8_STAGE(bufoff, gbase, voff) do { _Pragma("unroll") for (int _i = 0; _i < 2; ++_i) \
;         __builtin_amdgcn_global_load_lds((const unsigned*)((const char*)(gbase) + (voff)[_i]), (LAS unsigned*)(lds + (bufoff) + ldsw + _i * 8192), 16, 0, 0); } while (0)
; #define PG8_LDA(dst, b, h) do { _Pragma("unroll") for (int m = 0; m < 4; ++m) _Pragma("unroll") for (int k = 0; k < 2; ++k) dst[m][k] = *(const LAS bf16x8*)(lds + PG8_SA(b, h) + aoff + m * 2048 + k * 1024); } while (0)
; #define PG8_LDB(dst, b, h) do { _Pragma("unroll") for (int n = 0; n < 2; ++n) _Pragma("unroll") for (int k = 0; k < 2; ++k) dst[n][k] = *(const LAS bf16x8*)(lds + PG8_SB(b, h) + boff + n * 2048 + k * 1024); } while (0)
; #define PG8_WAIT_V(n) asm volatile("s_waitcnt vmcnt(" #n ")" ::: "memory")
; #define PG8_WAIT_L(n) asm volatile("s_waitcnt lgkmcnt(" #n ")" ::: "memory")
; #define PG8_BAR __builtin_amdgcn_s_barrier()
; #define PG8_SCHED __builtin_amdgcn_sched_barrier(0)
; template <class Epi, class Sched, bool F8 = false>
; __device__ __forceinline__ void gemm_phase(LAS unsigned char* lds, const Gemm g, const Sched& S, const Epi& E) {
;     ...
;         for (int t = 0; t < nt; t += 2) {
;             const bool last = (t == nt - 2);
;             const char* a1 = cA + (size_t)(t + 1) * kstep;
;             const char* a2 = last ? nA : cA + (size_t)(t + 2) * kstep; const char* b2 = last ? nB : cB + (size_t)(t + 2) * kstep;
;             const char* a3 = a2 + kstep; const char* b3 = b2 + kstep;
;             PG8_LDB(B0, 0, 0); PG8_LDB(B1, 0, 1); PG8_SCHED; PG8_LDA(At, 0, 0); PG8_STAGE(PG8_SA(1, 1), a1 + hstepA, voffA);
;             PG8_WAIT_V(8); PG8_WAIT_L(0); PG8_BAR; PG8_MMA(0, 0, At, B0); PG8_MMA(0, 1, At, B1); PG8_BAR; PG8_SCHED;
;             PG8_LDA(At, 0, 1); PG8_STAGE(PG8_SB(0, 0), b2, voffB); PG8_STAGE(PG8_SB(0, 1), b2 + hstepB, voffB); PG8_STAGE(PG8_SA(0, 0), a2, voffA);
;             PG8_WAIT_V(8); PG8_WAIT_L(0); PG8_BAR; PG8_MMA(1, 0, At, B0); PG8_MMA(1, 1, At, B1); PG8_BAR; PG8_SCHED;
.LBB0_144:
	ds_read_b128 v[72:75], v170
	ds_read_b128 v[76:79], v170 offset:1024
	ds_read_b128 v[80:83], v170 offset:2048
	ds_read_b128 v[88:91], v170 offset:3072
	ds_read_b128 v[162:165], v171
	ds_read_b128 v[174:177], v171 offset:1024
	ds_read_b128 v[178:181], v171 offset:2048
	ds_read_b128 v[182:185], v171 offset:3072
	s_add_u32 s30, s26, 0xfff80080
	s_addc_u32 s31, s27, -1
	s_cmp_eq_u32 s50, 28
	s_cselect_b32 s35, s7, s31
	s_cselect_b32 s34, s19, s30
	s_cselect_b32 s31, s17, s49
	s_cselect_b32 s30, s36, s37
	s_add_i32 m0, s29, 0xc000
	ds_read_b128 v[192:195], v172
	ds_read_b128 v[196:199], v172 offset:1024
	ds_read_b128 v[200:203], v172 offset:2048
	ds_read_b128 v[204:207], v172 offset:3072
	ds_read_b128 v[208:211], v172 offset:4096
	ds_read_b128 v[212:215], v172 offset:5120
	ds_read_b128 v[216:219], v172 offset:6144
	ds_read_b128 v[220:223], v172 offset:7168
	global_load_lds_dwordx4 v152, s[26:27]
	s_add_i32 m0, s29, 0xe000
	s_nop 0
	global_load_lds_dwordx4 v154, s[26:27]
	s_waitcnt vmcnt(8)
	s_waitcnt lgkmcnt(0)
	s_barrier
	s_setprio 1
	s_waitcnt lgkmcnt(0)
	v_mfma_f32_16x16x32_bf16 v[140:143], v[72:75], v[192:195], v[140:143]
	v_mfma_f32_16x16x32_bf16 v[136:139], v[80:83], v[192:195], v[136:139]
	v_mfma_f32_16x16x32_bf16 v[124:127], v[72:75], v[200:203], v[124:127]
	v_mfma_f32_16x16x32_bf16 v[120:123], v[80:83], v[200:203], v[120:123]
	v_mfma_f32_16x16x32_bf16 v[108:111], v[72:75], v[208:211], v[108:111]
	v_mfma_f32_16x16x32_bf16 v[104:107], v[80:83], v[208:211], v[104:107]
	v_mfma_f32_16x16x32_bf16 v[92:95], v[72:75], v[216:219], v[92:95]
	v_mfma_f32_16x16x32_bf16 v[84:87], v[80:83], v[216:219], v[84:87]
	v_mfma_f32_16x16x32_bf16 v[140:143], v[76:79], v[196:199], v[140:143]
	v_mfma_f32_16x16x32_bf16 v[136:139], v[88:91], v[196:199], v[136:139]
	v_mfma_f32_16x16x32_bf16 v[124:127], v[76:79], v[204:207], v[124:127]
	v_mfma_f32_16x16x32_bf16 v[120:123], v[88:91], v[204:207], v[120:123]
	v_mfma_f32_16x16x32_bf16 v[108:111], v[76:79], v[212:215], v[108:111]
	v_mfma_f32_16x16x32_bf16 v[104:107], v[88:91], v[212:215], v[104:107]
	v_mfma_f32_16x16x32_bf16 v[92:95], v[76:79], v[220:223], v[92:95]
	v_mfma_f32_16x16x32_bf16 v[84:87], v[88:91], v[220:223], v[84:87]
	s_setprio 0
	s_setprio 1
	v_mfma_f32_16x16x32_bf16 v[132:135], v[162:165], v[192:195], v[132:135]
	v_mfma_f32_16x16x32_bf16 v[128:131], v[178:181], v[192:195], v[128:131]
	v_mfma_f32_16x16x32_bf16 v[116:119], v[162:165], v[200:203], v[116:119]
	v_mfma_f32_16x16x32_bf16 v[112:115], v[178:181], v[200:203], v[112:115]
	v_mfma_f32_16x16x32_bf16 v[100:103], v[162:165], v[208:211], v[100:103]
	v_mfma_f32_16x16x32_bf16 v[96:99], v[178:181], v[208:211], v[96:99]
	v_mfma_f32_16x16x32_bf16 v[68:71], v[162:165], v[216:219], v[68:71]
	v_mfma_f32_16x16x32_bf16 v[64:67], v[178:181], v[216:219], v[64:67]
	v_mfma_f32_16x16x32_bf16 v[132:135], v[174:177], v[196:199], v[132:135]
	v_mfma_f32_16x16x32_bf16 v[128:131], v[182:185], v[196:199], v[128:131]
	v_mfma_f32_16x16x32_bf16 v[116:119], v[174:177], v[204:207], v[116:119]
	v_mfma_f32_16x16x32_bf16 v[112:115], v[182:185], v[204:207], v[112:115]
	v_mfma_f32_16x16x32_bf16 v[100:103], v[174:177], v[212:215], v[100:103]
	v_mfma_f32_16x16x32_bf16 v[96:99], v[182:185], v[212:215], v[96:99]
	v_mfma_f32_16x16x32_bf16 v[68:71], v[174:177], v[220:223], v[68:71]
	v_mfma_f32_16x16x32_bf16 v[64:67], v[182:185], v[220:223], v[64:67]
	s_setprio 0
	s_barrier
	s_add_i32 s51, s47, s38
	v_lshl_add_u64 v[166:167], s[30:31], 0, v[146:147]
	s_mov_b32 m0, s51
	ds_read_b128 v[192:195], v172 offset:16384
	ds_read_b128 v[196:199], v172 offset:17408
	ds_read_b128 v[200:203], v172 offset:18432
	ds_read_b128 v[204:207], v172 offset:19456
	ds_read_b128 v[208:211], v172 offset:20480
	ds_read_b128 v[212:215], v172 offset:21504
	ds_read_b128 v[216:219], v172 offset:22528
	ds_read_b128 v[220:223], v172 offset:23552
	global_load_lds_dwordx4 v[166:167], off
	s_add_i32 m0, s51, 0x2000
	s_add_u32 s56, s30, 0x80000
	v_lshl_add_u64 v[188:189], s[30:31], 0, v[150:151]
	s_addc_u32 s57, s31, 0
	s_add_i32 s51, s48, s38
	global_load_lds_dwordx4 v[188:189], off
	s_mov_b32 m0, s51
	v_lshl_add_u64 v[226:227], s[34:35], 0, v[148:149]
	global_load_lds_dwordx4 v146, s[56:57]
	s_add_i32 m0, s51, 0x2000
	s_nop 0
	global_load_lds_dwordx4 v150, s[56:57]
	v_lshl_add_u64 v[224:225], s[34:35], 0, v[144:145]
	s_mov_b32 m0, s29
	s_nop 0
	global_load_lds_dwordx4 v[224:225], off
	s_mov_b32 m0, s39
	s_nop 0
	global_load_lds_dwordx4 v[226:227], off
	s_waitcnt vmcnt(8)
	s_waitcnt lgkmcnt(0)
	s_barrier
	s_setprio 1
	s_waitcnt lgkmcnt(0)
	v_mfma_f32_16x16x32_bf16 v[60:63], v[72:75], v[192:195], v[60:63]
	v_mfma_f32_16x16x32_bf16 v[56:59], v[80:83], v[192:195], v[56:59]
	v_mfma_f32_16x16x32_bf16 v[44:47], v[72:75], v[200:203], v[44:47]
	v_mfma_f32_16x16x32_bf16 v[40:43], v[80:83], v[200:203], v[40:43]
	v_mfma_f32_16x16x32_bf16 v[28:31], v[72:75], v[208:211], v[28:31]
	v_mfma_f32_16x16x32_bf16 v[24:27], v[80:83], v[208:211], v[24:27]
	v_mfma_f32_16x16x32_bf16 v[12:15], v[72:75], v[216:219], v[12:15]
	v_mfma_f32_16x16x32_bf16 v[8:11], v[80:83], v[216:219], v[8:11]
	v_mfma_f32_16x16x32_bf16 v[60:63], v[76:79], v[196:199], v[60:63]
	v_mfma_f32_16x16x32_bf16 v[56:59], v[88:91], v[196:199], v[56:59]
	v_mfma_f32_16x16x32_bf16 v[44:47], v[76:79], v[204:207], v[44:47]
	v_mfma_f32_16x16x32_bf16 v[40:43], v[88:91], v[204:207], v[40:43]
	v_mfma_f32_16x16x32_bf16 v[28:31], v[76:79], v[212:215], v[28:31]
	v_mfma_f32_16x16x32_bf16 v[24:27], v[88:91], v[212:215], v[24:27]
	v_mfma_f32_16x16x32_bf16 v[12:15], v[76:79], v[220:223], v[12:15]
	v_mfma_f32_16x16x32_bf16 v[8:11], v[88:91], v[220:223], v[8:11]
	s_setprio 0
	s_setprio 1
	v_mfma_f32_16x16x32_bf16 v[52:55], v[162:165], v[192:195], v[52:55]
	v_mfma_f32_16x16x32_bf16 v[48:51], v[178:181], v[192:195], v[48:51]
	v_mfma_f32_16x16x32_bf16 v[36:39], v[162:165], v[200:203], v[36:39]
	v_mfma_f32_16x16x32_bf16 v[32:35], v[178:181], v[200:203], v[32:35]
	v_mfma_f32_16x16x32_bf16 v[20:23], v[162:165], v[208:211], v[20:23]
	v_mfma_f32_16x16x32_bf16 v[16:19], v[178:181], v[208:211], v[16:19]
	v_mfma_f32_16x16x32_bf16 v[4:7], v[162:165], v[216:219], v[4:7]
	v_mfma_f32_16x16x32_bf16 v[0:3], v[178:181], v[216:219], v[0:3]
	v_mfma_f32_16x16x32_bf16 v[52:55], v[174:177], v[196:199], v[52:55]
	v_mfma_f32_16x16x32_bf16 v[48:51], v[182:185], v[196:199], v[48:51]
	v_mfma_f32_16x16x32_bf16 v[36:39], v[174:177], v[204:207], v[36:39]
	v_mfma_f32_16x16x32_bf16 v[32:35], v[182:185], v[204:207], v[32:35]
	v_mfma_f32_16x16x32_bf16 v[20:23], v[174:177], v[212:215], v[20:23]
	v_mfma_f32_16x16x32_bf16 v[16:19], v[182:185], v[212:215], v[16:19]
	v_mfma_f32_16x16x32_bf16 v[4:7], v[174:177], v[220:223], v[4:7]
	v_mfma_f32_16x16x32_bf16 v[0:3], v[182:185], v[220:223], v[0:3]
	s_setprio 0
	s_barrier
; #define PG8_STAGE(bufoff, gbase, voff) do { _Pragma("unroll") for (int _i = 0; _i < 2; ++_i) \
;         __builtin_amdgcn_global_load_lds((const unsigned*)((const char*)(gbase) + (voff)[_i]), (LAS unsigned*)(lds + (bufoff) + ldsw + _i * 8192), 16, 0, 0); } while (0)
; #define PG8_LDA(dst, b, h) do { _Pragma("unroll") for (int m = 0; m < 4; ++m) _Pragma("unroll") for (int k = 0; k < 2; ++k) dst[m][k] = *(const LAS bf16x8*)(lds + PG8_SA(b, h) + aoff + m * 2048 + k * 1024); } while (0)
; #define PG8_LDB(dst, b, h) do { _Pragma("unroll") for (int n = 0; n < 2; ++n) _Pragma("unroll") for (int k = 0; k < 2; ++k) dst[n][k] = *(const LAS bf16x8*)(lds + PG8_SB(b, h) + boff + n * 2048 + k * 1024); } while (0)
; #define PG8_WAIT_V(n) asm volatile("s_waitcnt vmcnt(" #n ")" ::: "memory")
; #define PG8_WAIT_L(n) asm volatile("s_waitcnt lgkmcnt(" #n ")" ::: "memory")
; #define PG8_BAR __builtin_amdgcn_s_barrier()
; #define PG8_SCHED __builtin_amdgcn_sched_barrier(0)
; template <class Epi, class Sched, bool F8 = false>
; __device__ __forceinline__ void gemm_phase(LAS unsigned char* lds, const Gemm g, const Sched& S, const Epi& E) {
;     ...
;             PG8_LDB(B0, 1, 0); PG8_LDB(B1, 1, 1); PG8_SCHED; PG8_LDA(At, 1, 0); PG8_STAGE(PG8_SA(0, 1), a2 + hstepA, voffA);
;             PG8_WAIT_V(8); PG8_WAIT_L(0); PG8_BAR; PG8_MMA(0, 0, At, B0); PG8_MMA(0, 1, At, B1); PG8_BAR; PG8_SCHED;
;             PG8_LDA(At, 1, 1); PG8_STAGE(PG8_SB(1, 0), b3, voffB); PG8_STAGE(PG8_SB(1, 1), b3 + hstepB, voffB); PG8_STAGE(PG8_SA(1, 0), a3, voffA);
;             PG8_WAIT_V(8); PG8_WAIT_L(0); PG8_BAR; PG8_MMA(1, 0, At, B0); PG8_MMA(1, 1, At, B1); PG8_BAR; PG8_SCHED;
;         }
	s_add_i32 s51, 0, 0x18000
	s_add_i32 s53, 0, 0x1c000
	v_add_u32_e32 v88, s51, v168
	v_add_u32_e32 v173, s53, v168
	ds_read_b128 v[72:75], v88
	ds_read_b128 v[76:79], v88 offset:1024
	ds_read_b128 v[80:83], v88 offset:2048
	ds_read_b128 v[88:91], v88 offset:3072
	ds_read_b128 v[162:165], v173
	ds_read_b128 v[174:177], v173 offset:1024
	ds_read_b128 v[178:181], v173 offset:2048
	ds_read_b128 v[182:185], v173 offset:3072
	s_add_u32 s34, s34, 0x80000
	s_addc_u32 s35, s35, 0
	s_mov_b32 m0, s40
	ds_read_b128 v[192:195], v172 offset:32768
	ds_read_b128 v[196:199], v172 offset:33792
	ds_read_b128 v[200:203], v172 offset:34816
	ds_read_b128 v[204:207], v172 offset:35840
	ds_read_b128 v[208:211], v172 offset:36864
	ds_read_b128 v[212:215], v172 offset:37888
	ds_read_b128 v[216:219], v172 offset:38912
	ds_read_b128 v[220:223], v172 offset:39936
	global_load_lds_dwordx4 v144, s[34:35]
	s_mov_b32 m0, s41
	s_nop 0
	global_load_lds_dwordx4 v148, s[34:35]
	s_waitcnt vmcnt(8)
	s_waitcnt lgkmcnt(0)
	s_barrier
	s_setprio 1
	s_waitcnt lgkmcnt(0)
	v_mfma_f32_16x16x32_bf16 v[140:143], v[72:75], v[192:195], v[140:143]
	v_mfma_f32_16x16x32_bf16 v[136:139], v[80:83], v[192:195], v[136:139]
	v_mfma_f32_16x16x32_bf16 v[124:127], v[72:75], v[200:203], v[124:127]
	v_mfma_f32_16x16x32_bf16 v[120:123], v[80:83], v[200:203], v[120:123]
	v_mfma_f32_16x16x32_bf16 v[108:111], v[72:75], v[208:211], v[108:111]
	v_mfma_f32_16x16x32_bf16 v[104:107], v[80:83], v[208:211], v[104:107]
	v_mfma_f32_16x16x32_bf16 v[92:95], v[72:75], v[216:219], v[92:95]
	v_mfma_f32_16x16x32_bf16 v[84:87], v[80:83], v[216:219], v[84:87]
	v_mfma_f32_16x16x32_bf16 v[140:143], v[76:79], v[196:199], v[140:143]
	v_mfma_f32_16x16x32_bf16 v[136:139], v[88:91], v[196:199], v[136:139]
	v_mfma_f32_16x16x32_bf16 v[124:127], v[76:79], v[204:207], v[124:127]
	v_mfma_f32_16x16x32_bf16 v[120:123], v[88:91], v[204:207], v[120:123]
	v_mfma_f32_16x16x32_bf16 v[108:111], v[76:79], v[212:215], v[108:111]
	v_mfma_f32_16x16x32_bf16 v[104:107], v[88:91], v[212:215], v[104:107]
	v_mfma_f32_16x16x32_bf16 v[92:95], v[76:79], v[220:223], v[92:95]
	v_mfma_f32_16x16x32_bf16 v[84:87], v[88:91], v[220:223], v[84:87]
	s_setprio 0
	s_setprio 1
	v_mfma_f32_16x16x32_bf16 v[132:135], v[162:165], v[192:195], v[132:135]
	v_mfma_f32_16x16x32_bf16 v[128:131], v[178:181], v[192:195], v[128:131]
	v_mfma_f32_16x16x32_bf16 v[116:119], v[162:165], v[200:203], v[116:119]
	v_mfma_f32_16x16x32_bf16 v[112:115], v[178:181], v[200:203], v[112:115]
	v_mfma_f32_16x16x32_bf16 v[100:103], v[162:165], v[208:211], v[100:103]
	v_mfma_f32_16x16x32_bf16 v[96:99], v[178:181], v[208:211], v[96:99]
	v_mfma_f32_16x16x32_bf16 v[68:71], v[162:165], v[216:219], v[68:71]
	v_mfma_f32_16x16x32_bf16 v[64:67], v[178:181], v[216:219], v[64:67]
	v_mfma_f32_16x16x32_bf16 v[132:135], v[174:177], v[196:199], v[132:135]
	v_mfma_f32_16x16x32_bf16 v[128:131], v[182:185], v[196:199], v[128:131]
	v_mfma_f32_16x16x32_bf16 v[116:119], v[174:177], v[204:207], v[116:119]
	v_mfma_f32_16x16x32_bf16 v[112:115], v[182:185], v[204:207], v[112:115]
	v_mfma_f32_16x16x32_bf16 v[100:103], v[174:177], v[212:215], v[100:103]
	v_mfma_f32_16x16x32_bf16 v[96:99], v[182:185], v[212:215], v[96:99]
	v_mfma_f32_16x16x32_bf16 v[68:71], v[174:177], v[220:223], v[68:71]
	v_mfma_f32_16x16x32_bf16 v[64:67], v[182:185], v[220:223], v[64:67]
	s_setprio 0
	s_barrier
	s_add_i32 s34, s51, s38
	s_add_i32 m0, s34, 0xffffff80
	ds_read_b128 v[192:195], v172 offset:49152
	ds_read_b128 v[196:199], v172 offset:50176
	ds_read_b128 v[200:203], v172 offset:51200
	ds_read_b128 v[204:207], v172 offset:52224
	ds_read_b128 v[208:211], v172 offset:53248
	ds_read_b128 v[212:215], v172 offset:54272
	ds_read_b128 v[216:219], v172 offset:55296
	ds_read_b128 v[220:223], v172 offset:56320
	global_load_lds_dwordx4 v[166:167], off offset:128
	s_add_i32 m0, s34, 0x1f80
	s_add_u32 s30, s30, 0x80080
	s_addc_u32 s31, s31, 0
	s_add_i32 s34, s53, s38
	global_load_lds_dwordx4 v[188:189], off offset:128
	s_mov_b32 m0, s34
	s_nop 0
	global_load_lds_dwordx4 v146, s[30:31]
	s_add_i32 m0, s34, 0x2000
	s_nop 0
	global_load_lds_dwordx4 v150, s[30:31]
	s_add_i32 m0, s43, 0xffffff80
	s_nop 0
	global_load_lds_dwordx4 v[224:225], off offset:128
	s_add_i32 m0, s44, 0xffffff80
	s_nop 0
	global_load_lds_dwordx4 v[226:227], off offset:128
	s_waitcnt vmcnt(8)
	s_waitcnt lgkmcnt(0)
	s_barrier
	s_setprio 1
	s_waitcnt lgkmcnt(0)
	v_mfma_f32_16x16x32_bf16 v[60:63], v[72:75], v[192:195], v[60:63]
	v_mfma_f32_16x16x32_bf16 v[56:59], v[80:83], v[192:195], v[56:59]
	v_mfma_f32_16x16x32_bf16 v[44:47], v[72:75], v[200:203], v[44:47]
	v_mfma_f32_16x16x32_bf16 v[40:43], v[80:83], v[200:203], v[40:43]
	v_mfma_f32_16x16x32_bf16 v[28:31], v[72:75], v[208:211], v[28:31]
	v_mfma_f32_16x16x32_bf16 v[24:27], v[80:83], v[208:211], v[24:27]
	v_mfma_f32_16x16x32_bf16 v[12:15], v[72:75], v[216:219], v[12:15]
	v_mfma_f32_16x16x32_bf16 v[8:11], v[80:83], v[216:219], v[8:11]
	v_mfma_f32_16x16x32_bf16 v[60:63], v[76:79], v[196:199], v[60:63]
	v_mfma_f32_16x16x32_bf16 v[56:59], v[88:91], v[196:199], v[56:59]
	v_mfma_f32_16x16x32_bf16 v[44:47], v[76:79], v[204:207], v[44:47]
	v_mfma_f32_16x16x32_bf16 v[40:43], v[88:91], v[204:207], v[40:43]
	v_mfma_f32_16x16x32_bf16 v[28:31], v[76:79], v[212:215], v[28:31]
	v_mfma_f32_16x16x32_bf16 v[24:27], v[88:91], v[212:215], v[24:27]
	v_mfma_f32_16x16x32_bf16 v[12:15], v[76:79], v[220:223], v[12:15]
	v_mfma_f32_16x16x32_bf16 v[8:11], v[88:91], v[220:223], v[8:11]
	s_setprio 0
	s_setprio 1
	v_mfma_f32_16x16x32_bf16 v[52:55], v[162:165], v[192:195], v[52:55]
	v_mfma_f32_16x16x32_bf16 v[48:51], v[178:181], v[192:195], v[48:51]
	v_mfma_f32_16x16x32_bf16 v[36:39], v[162:165], v[200:203], v[36:39]
	v_mfma_f32_16x16x32_bf16 v[32:35], v[178:181], v[200:203], v[32:35]
	v_mfma_f32_16x16x32_bf16 v[20:23], v[162:165], v[208:211], v[20:23]
	v_mfma_f32_16x16x32_bf16 v[16:19], v[178:181], v[208:211], v[16:19]
	v_mfma_f32_16x16x32_bf16 v[4:7], v[162:165], v[216:219], v[4:7]
	v_mfma_f32_16x16x32_bf16 v[0:3], v[178:181], v[216:219], v[0:3]
	v_mfma_f32_16x16x32_bf16 v[52:55], v[174:177], v[196:199], v[52:55]
	v_mfma_f32_16x16x32_bf16 v[48:51], v[182:185], v[196:199], v[48:51]
	v_mfma_f32_16x16x32_bf16 v[36:39], v[174:177], v[204:207], v[36:39]
	v_mfma_f32_16x16x32_bf16 v[32:35], v[182:185], v[204:207], v[32:35]
	v_mfma_f32_16x16x32_bf16 v[20:23], v[174:177], v[212:215], v[20:23]
	v_mfma_f32_16x16x32_bf16 v[16:19], v[182:185], v[212:215], v[16:19]
	v_mfma_f32_16x16x32_bf16 v[4:7], v[174:177], v[220:223], v[4:7]
	v_mfma_f32_16x16x32_bf16 v[0:3], v[182:185], v[220:223], v[0:3]
	s_setprio 0
	s_add_i32 s50, s50, 2
	s_add_u32 s26, s26, 0x100
	s_addc_u32 s27, s27, 0
	s_add_u32 s37, s37, 0x100
	s_addc_u32 s49, s49, 0
	s_cmp_gt_u32 s50, 29
	s_barrier
	s_cbranch_scc0 .LBB0_144
	s_and_b64 vcc, exec, s[14:15]
	s_cbranch_vccz .LBB0_147
	s_barrier

; #define PG8_STAGE(bufoff, gbase, voff) do { _Pragma("unroll") for (int _i = 0; _i < 2; ++_i) \
;         __builtin_amdgcn_global_load_lds((const unsigned*)((const char*)(gbase) + (voff)[_i]), (LAS unsigned*)(lds + (bufoff) + ldsw + _i * 8192), 16, 0, 0); } while (0)
; #define PG8_LDA(dst, b, h) do { _Pragma("unroll") for (int m = 0; m < 4; ++m) _Pragma("unroll") for (int k = 0; k < 2; ++k) dst[m][k] = *(const LAS bf16x8*)(lds + PG8_SA(b, h) + aoff + m * 2048 + k * 1024); } while (0)
; #define PG8_LDB(dst, b, h) do { _Pragma("unroll") for (int n = 0; n < 2; ++n) _Pragma("unroll") for (int k = 0; k < 2; ++k) dst[n][k] = *(const LAS bf16x8*)(lds + PG8_SB(b, h) + boff + n * 2048 + k * 1024); } while (0)
; #define PG8_WAIT_V(n) asm volatile("s_waitcnt vmcnt(" #n ")" ::: "memory")
; #define PG8_WAIT_L(n) asm volatile("s_waitcnt lgkmcnt(" #n ")" ::: "memory")
; #define PG8_BAR __builtin_amdgcn_s_barrier()
; #define PG8_SCHED __builtin_amdgcn_sched_barrier(0)
; template <class Epi, class Sched, bool F8 = false>
; __device__ __forceinline__ void gemm_phase(LAS unsigned char* lds, const Gemm g, const Sched& S, const Epi& E) {
;     ...
;         for (int t = 0; t < nt; t += 2) {
;             const bool last = (t == nt - 2);
;             const char* a1 = cA + (size_t)(t + 1) * kstep;
;             const char* a2 = last ? nA : cA + (size_t)(t + 2) * kstep; const char* b2 = last ? nB : cB + (size_t)(t + 2) * kstep;
;             const char* a3 = a2 + kstep; const char* b3 = b2 + kstep;
;             PG8_LDB(B0, 0, 0); PG8_LDB(B1, 0, 1); PG8_SCHED; PG8_LDA(At, 0, 0); PG8_STAGE(PG8_SA(1, 1), a1 + hstepA, voffA);
;             PG8_WAIT_V(8); PG8_WAIT_L(0); PG8_BAR; PG8_MMA(0, 0, At, B0); PG8_MMA(0, 1, At, B1); PG8_BAR; PG8_SCHED;
;             PG8_LDA(At, 0, 1); PG8_STAGE(PG8_SB(0, 0), b2, voffB); PG8_STAGE(PG8_SB(0, 1), b2 + hstepB, voffB); PG8_STAGE(PG8_SA(0, 0), a2, voffA);
;             PG8_WAIT_V(8); PG8_WAIT_L(0); PG8_BAR; PG8_MMA(1, 0, At, B0); PG8_MMA(1, 1, At, B1); PG8_BAR; PG8_SCHED;
.LBB0_208:
	ds_read_b128 v[152:155], v189
	ds_read_b128 v[156:159], v189 offset:1024
	ds_read_b128 v[144:147], v189 offset:2048
	ds_read_b128 v[148:151], v189 offset:3072
	ds_read_b128 v[136:139], v191
	ds_read_b128 v[140:143], v191 offset:1024
	ds_read_b128 v[128:131], v191 offset:2048
	ds_read_b128 v[132:135], v191 offset:3072
	s_add_u32 s30, s28, 0xfffc0080
	s_addc_u32 s31, s29, -1
	s_cmp_eq_u32 s53, 12
	s_cselect_b32 s35, s21, s31
	s_cselect_b32 s34, s48, s30
	s_cselect_b32 s31, s19, s51
	s_cselect_b32 s30, s49, s50
	s_add_i32 m0, s27, 0xc000
	ds_read_b128 v[178:181], v192
	ds_read_b128 v[182:185], v192 offset:1024
	ds_read_b128 v[194:197], v192 offset:2048
	ds_read_b128 v[198:201], v192 offset:3072
	ds_read_b128 v[202:205], v192 offset:4096
	ds_read_b128 v[206:209], v192 offset:5120
	ds_read_b128 v[210:213], v192 offset:6144
	ds_read_b128 v[214:217], v192 offset:7168
	global_load_lds_dwordx4 v170, s[28:29]
	s_add_i32 m0, s27, 0xe000
	s_nop 0
	global_load_lds_dwordx4 v172, s[28:29]
	s_waitcnt vmcnt(8)
	s_waitcnt lgkmcnt(0)
	s_barrier
	s_setprio 1
	s_waitcnt lgkmcnt(0)
	v_mfma_scale_f32_16x16x128_f8f6f4 v[124:127], v[152:159], v[178:185], v[124:127], v254, v254 op_sel_hi:[0,0,0]
	v_mfma_scale_f32_16x16x128_f8f6f4 v[120:123], v[144:151], v[178:185], v[120:123], v254, v254 op_sel_hi:[0,0,0]
	v_mfma_scale_f32_16x16x128_f8f6f4 v[108:111], v[152:159], v[194:201], v[108:111], v254, v254 op_sel_hi:[0,0,0]
	v_mfma_scale_f32_16x16x128_f8f6f4 v[104:107], v[144:151], v[194:201], v[104:107], v254, v254 op_sel_hi:[0,0,0]
	v_mfma_scale_f32_16x16x128_f8f6f4 v[92:95], v[152:159], v[202:209], v[92:95], v254, v254 op_sel_hi:[0,0,0]
	v_mfma_scale_f32_16x16x128_f8f6f4 v[88:91], v[144:151], v[202:209], v[88:91], v254, v254 op_sel_hi:[0,0,0]
	v_mfma_scale_f32_16x16x128_f8f6f4 v[76:79], v[152:159], v[210:217], v[76:79], v254, v254 op_sel_hi:[0,0,0]
	v_mfma_scale_f32_16x16x128_f8f6f4 v[72:75], v[144:151], v[210:217], v[72:75], v254, v254 op_sel_hi:[0,0,0]
	s_setprio 0
	s_setprio 1
	v_mfma_scale_f32_16x16x128_f8f6f4 v[116:119], v[136:143], v[178:185], v[116:119], v254, v254 op_sel_hi:[0,0,0]
	v_mfma_scale_f32_16x16x128_f8f6f4 v[112:115], v[128:135], v[178:185], v[112:115], v254, v254 op_sel_hi:[0,0,0]
	v_mfma_scale_f32_16x16x128_f8f6f4 v[100:103], v[136:143], v[194:201], v[100:103], v254, v254 op_sel_hi:[0,0,0]
	v_mfma_scale_f32_16x16x128_f8f6f4 v[96:99], v[128:135], v[194:201], v[96:99], v254, v254 op_sel_hi:[0,0,0]
	v_mfma_scale_f32_16x16x128_f8f6f4 v[84:87], v[136:143], v[202:209], v[84:87], v254, v254 op_sel_hi:[0,0,0]
	v_mfma_scale_f32_16x16x128_f8f6f4 v[80:83], v[128:135], v[202:209], v[80:83], v254, v254 op_sel_hi:[0,0,0]
	v_mfma_scale_f32_16x16x128_f8f6f4 v[68:71], v[136:143], v[210:217], v[68:71], v254, v254 op_sel_hi:[0,0,0]
	v_mfma_scale_f32_16x16x128_f8f6f4 v[64:67], v[128:135], v[210:217], v[64:67], v254, v254 op_sel_hi:[0,0,0]
	s_setprio 0
	s_barrier
	s_add_i32 s56, s43, s17
	v_lshl_add_u64 v[178:179], s[30:31], 0, v[166:167]
	s_mov_b32 m0, s56
	ds_read_b128 v[194:197], v192 offset:16384
	ds_read_b128 v[198:201], v192 offset:17408
	ds_read_b128 v[202:205], v192 offset:18432
	ds_read_b128 v[206:209], v192 offset:19456
	ds_read_b128 v[210:213], v192 offset:20480
	ds_read_b128 v[214:217], v192 offset:21504
	ds_read_b128 v[218:221], v192 offset:22528
	ds_read_b128 v[222:225], v192 offset:23552
	global_load_lds_dwordx4 v[178:179], off
	s_add_i32 m0, s56, 0x2000
	s_add_u32 s56, s30, 0x40000
	v_lshl_add_u64 v[180:181], s[30:31], 0, v[162:163]
	s_addc_u32 s57, s31, 0
	s_add_i32 s58, s44, s17
	global_load_lds_dwordx4 v[180:181], off
	s_mov_b32 m0, s58
	v_lshl_add_u64 v[184:185], s[34:35], 0, v[164:165]
	global_load_lds_dwordx4 v166, s[56:57]
	s_add_i32 m0, s58, 0x2000
	s_nop 0
	global_load_lds_dwordx4 v162, s[56:57]
	v_lshl_add_u64 v[182:183], s[34:35], 0, v[168:169]
	s_mov_b32 m0, s27
	s_nop 0
	global_load_lds_dwordx4 v[182:183], off
	s_mov_b32 m0, s37
	s_nop 0
	global_load_lds_dwordx4 v[184:185], off
	s_waitcnt vmcnt(8)
	s_waitcnt lgkmcnt(0)
	s_barrier
	s_setprio 1
	s_waitcnt lgkmcnt(0)
	v_mfma_scale_f32_16x16x128_f8f6f4 v[60:63], v[152:159], v[194:201], v[60:63], v254, v254 op_sel_hi:[0,0,0]
	v_mfma_scale_f32_16x16x128_f8f6f4 v[56:59], v[144:151], v[194:201], v[56:59], v254, v254 op_sel_hi:[0,0,0]
	v_mfma_scale_f32_16x16x128_f8f6f4 v[44:47], v[152:159], v[202:209], v[44:47], v254, v254 op_sel_hi:[0,0,0]
	v_mfma_scale_f32_16x16x128_f8f6f4 v[40:43], v[144:151], v[202:209], v[40:43], v254, v254 op_sel_hi:[0,0,0]
	v_mfma_scale_f32_16x16x128_f8f6f4 v[28:31], v[152:159], v[210:217], v[28:31], v254, v254 op_sel_hi:[0,0,0]
	v_mfma_scale_f32_16x16x128_f8f6f4 v[24:27], v[144:151], v[210:217], v[24:27], v254, v254 op_sel_hi:[0,0,0]
	v_mfma_scale_f32_16x16x128_f8f6f4 v[12:15], v[152:159], v[218:225], v[12:15], v254, v254 op_sel_hi:[0,0,0]
	v_mfma_scale_f32_16x16x128_f8f6f4 v[8:11], v[144:151], v[218:225], v[8:11], v254, v254 op_sel_hi:[0,0,0]
	s_setprio 0
	s_setprio 1
	v_mfma_scale_f32_16x16x128_f8f6f4 v[52:55], v[136:143], v[194:201], v[52:55], v254, v254 op_sel_hi:[0,0,0]
	v_mfma_scale_f32_16x16x128_f8f6f4 v[48:51], v[128:135], v[194:201], v[48:51], v254, v254 op_sel_hi:[0,0,0]
	v_mfma_scale_f32_16x16x128_f8f6f4 v[36:39], v[136:143], v[202:209], v[36:39], v254, v254 op_sel_hi:[0,0,0]
	v_mfma_scale_f32_16x16x128_f8f6f4 v[32:35], v[128:135], v[202:209], v[32:35], v254, v254 op_sel_hi:[0,0,0]
	v_mfma_scale_f32_16x16x128_f8f6f4 v[20:23], v[136:143], v[210:217], v[20:23], v254, v254 op_sel_hi:[0,0,0]
	v_mfma_scale_f32_16x16x128_f8f6f4 v[16:19], v[128:135], v[210:217], v[16:19], v254, v254 op_sel_hi:[0,0,0]
	v_mfma_scale_f32_16x16x128_f8f6f4 v[4:7], v[136:143], v[218:225], v[4:7], v254, v254 op_sel_hi:[0,0,0]
	v_mfma_scale_f32_16x16x128_f8f6f4 v[0:3], v[128:135], v[218:225], v[0:3], v254, v254 op_sel_hi:[0,0,0]
	s_setprio 0
	s_barrier
; #define PG8_STAGE(bufoff, gbase, voff) do { _Pragma("unroll") for (int _i = 0; _i < 2; ++_i) \
;         __builtin_amdgcn_global_load_lds((const unsigned*)((const char*)(gbase) + (voff)[_i]), (LAS unsigned*)(lds + (bufoff) + ldsw + _i * 8192), 16, 0, 0); } while (0)
; #define PG8_LDA(dst, b, h) do { _Pragma("unroll") for (int m = 0; m < 4; ++m) _Pragma("unroll") for (int k = 0; k < 2; ++k) dst[m][k] = *(const LAS bf16x8*)(lds + PG8_SA(b, h) + aoff + m * 2048 + k * 1024); } while (0)
; #define PG8_LDB(dst, b, h) do { _Pragma("unroll") for (int n = 0; n < 2; ++n) _Pragma("unroll") for (int k = 0; k < 2; ++k) dst[n][k] = *(const LAS bf16x8*)(lds + PG8_SB(b, h) + boff + n * 2048 + k * 1024); } while (0)
; #define PG8_WAIT_V(n) asm volatile("s_waitcnt vmcnt(" #n ")" ::: "memory")
; #define PG8_WAIT_L(n) asm volatile("s_waitcnt lgkmcnt(" #n ")" ::: "memory")
; #define PG8_BAR __builtin_amdgcn_s_barrier()
; #define PG8_SCHED __builtin_amdgcn_sched_barrier(0)
; template <class Epi, class Sched, bool F8 = false>
; __device__ __forceinline__ void gemm_phase(LAS unsigned char* lds, const Gemm g, const Sched& S, const Epi& E) {
;     ...
;             PG8_LDB(B0, 1, 0); PG8_LDB(B1, 1, 1); PG8_SCHED; PG8_LDA(At, 1, 0); PG8_STAGE(PG8_SA(0, 1), a2 + hstepA, voffA);
;             PG8_WAIT_V(8); PG8_WAIT_L(0); PG8_BAR; PG8_MMA(0, 0, At, B0); PG8_MMA(0, 1, At, B1); PG8_BAR; PG8_SCHED;
;             PG8_LDA(At, 1, 1); PG8_STAGE(PG8_SB(1, 0), b3, voffB); PG8_STAGE(PG8_SB(1, 1), b3 + hstepB, voffB); PG8_STAGE(PG8_SA(1, 0), a3, voffA);
;             PG8_WAIT_V(8); PG8_WAIT_L(0); PG8_BAR; PG8_MMA(1, 0, At, B0); PG8_MMA(1, 1, At, B1); PG8_BAR; PG8_SCHED;
;         }
	s_add_i32 s56, 0, 0x18000
	v_add_u32_e32 v128, s56, v187
	s_add_i32 s57, 0, 0x1c000
	ds_read_b128 v[152:155], v128
	ds_read_b128 v[156:159], v128 offset:1024
	ds_read_b128 v[144:147], v128 offset:2048
	ds_read_b128 v[148:151], v128 offset:3072
	v_add_u32_e32 v128, s57, v187
	ds_read_b128 v[136:139], v128
	ds_read_b128 v[140:143], v128 offset:1024
	ds_read_b128 v[132:135], v128 offset:3072
	ds_read_b128 v[128:131], v128 offset:2048
	s_add_u32 s34, s34, 0x40000
	s_addc_u32 s35, s35, 0
	s_mov_b32 m0, s38
	ds_read_b128 v[194:197], v192 offset:32768
	ds_read_b128 v[198:201], v192 offset:33792
	ds_read_b128 v[202:205], v192 offset:34816
	ds_read_b128 v[206:209], v192 offset:35840
	ds_read_b128 v[210:213], v192 offset:36864
	ds_read_b128 v[214:217], v192 offset:37888
	ds_read_b128 v[218:221], v192 offset:38912
	ds_read_b128 v[222:225], v192 offset:39936
	global_load_lds_dwordx4 v168, s[34:35]
	s_mov_b32 m0, s39
	s_nop 0
	global_load_lds_dwordx4 v164, s[34:35]
	s_waitcnt vmcnt(8)
	s_waitcnt lgkmcnt(0)
	s_barrier
	s_setprio 1
	s_waitcnt lgkmcnt(0)
	v_mfma_scale_f32_16x16x128_f8f6f4 v[124:127], v[152:159], v[194:201], v[124:127], v254, v254 op_sel_hi:[0,0,0]
	v_mfma_scale_f32_16x16x128_f8f6f4 v[120:123], v[144:151], v[194:201], v[120:123], v254, v254 op_sel_hi:[0,0,0]
	v_mfma_scale_f32_16x16x128_f8f6f4 v[108:111], v[152:159], v[202:209], v[108:111], v254, v254 op_sel_hi:[0,0,0]
	v_mfma_scale_f32_16x16x128_f8f6f4 v[104:107], v[144:151], v[202:209], v[104:107], v254, v254 op_sel_hi:[0,0,0]
	v_mfma_scale_f32_16x16x128_f8f6f4 v[92:95], v[152:159], v[210:217], v[92:95], v254, v254 op_sel_hi:[0,0,0]
	v_mfma_scale_f32_16x16x128_f8f6f4 v[88:91], v[144:151], v[210:217], v[88:91], v254, v254 op_sel_hi:[0,0,0]
	v_mfma_scale_f32_16x16x128_f8f6f4 v[76:79], v[152:159], v[218:225], v[76:79], v254, v254 op_sel_hi:[0,0,0]
	v_mfma_scale_f32_16x16x128_f8f6f4 v[72:75], v[144:151], v[218:225], v[72:75], v254, v254 op_sel_hi:[0,0,0]
	s_setprio 0
	s_setprio 1
	v_mfma_scale_f32_16x16x128_f8f6f4 v[116:119], v[136:143], v[194:201], v[116:119], v254, v254 op_sel_hi:[0,0,0]
	v_mfma_scale_f32_16x16x128_f8f6f4 v[112:115], v[128:135], v[194:201], v[112:115], v254, v254 op_sel_hi:[0,0,0]
	v_mfma_scale_f32_16x16x128_f8f6f4 v[100:103], v[136:143], v[202:209], v[100:103], v254, v254 op_sel_hi:[0,0,0]
	v_mfma_scale_f32_16x16x128_f8f6f4 v[96:99], v[128:135], v[202:209], v[96:99], v254, v254 op_sel_hi:[0,0,0]
	v_mfma_scale_f32_16x16x128_f8f6f4 v[84:87], v[136:143], v[210:217], v[84:87], v254, v254 op_sel_hi:[0,0,0]
	v_mfma_scale_f32_16x16x128_f8f6f4 v[80:83], v[128:135], v[210:217], v[80:83], v254, v254 op_sel_hi:[0,0,0]
	v_mfma_scale_f32_16x16x128_f8f6f4 v[68:71], v[136:143], v[218:225], v[68:71], v254, v254 op_sel_hi:[0,0,0]
	v_mfma_scale_f32_16x16x128_f8f6f4 v[64:67], v[128:135], v[218:225], v[64:67], v254, v254 op_sel_hi:[0,0,0]
	s_setprio 0
	s_barrier
	s_add_i32 s34, s56, s17
	s_add_i32 m0, s34, 0xffffff80
	ds_read_b128 v[194:197], v192 offset:49152
	ds_read_b128 v[198:201], v192 offset:50176
	ds_read_b128 v[202:205], v192 offset:51200
	ds_read_b128 v[206:209], v192 offset:52224
	ds_read_b128 v[210:213], v192 offset:53248
	ds_read_b128 v[214:217], v192 offset:54272
	ds_read_b128 v[218:221], v192 offset:55296
	ds_read_b128 v[222:225], v192 offset:56320
	global_load_lds_dwordx4 v[178:179], off offset:128
	s_add_i32 m0, s34, 0x1f80
	s_add_u32 s30, s30, 0x40080
	s_addc_u32 s31, s31, 0
	s_add_i32 s34, s57, s17
	global_load_lds_dwordx4 v[180:181], off offset:128
	s_mov_b32 m0, s34
	s_nop 0
	global_load_lds_dwordx4 v166, s[30:31]
	s_add_i32 m0, s34, 0x2000
	s_nop 0
	global_load_lds_dwordx4 v162, s[30:31]
	s_add_i32 m0, s41, 0xffffff80
	s_nop 0
	global_load_lds_dwordx4 v[182:183], off offset:128
	s_add_i32 m0, s42, 0xffffff80
	s_nop 0
	global_load_lds_dwordx4 v[184:185], off offset:128
	s_waitcnt vmcnt(8)
	s_waitcnt lgkmcnt(0)
	s_barrier
	s_setprio 1
	s_waitcnt lgkmcnt(0)
	v_mfma_scale_f32_16x16x128_f8f6f4 v[60:63], v[152:159], v[194:201], v[60:63], v254, v254 op_sel_hi:[0,0,0]
	v_mfma_scale_f32_16x16x128_f8f6f4 v[56:59], v[144:151], v[194:201], v[56:59], v254, v254 op_sel_hi:[0,0,0]
	v_mfma_scale_f32_16x16x128_f8f6f4 v[44:47], v[152:159], v[202:209], v[44:47], v254, v254 op_sel_hi:[0,0,0]
	v_mfma_scale_f32_16x16x128_f8f6f4 v[40:43], v[144:151], v[202:209], v[40:43], v254, v254 op_sel_hi:[0,0,0]
	v_mfma_scale_f32_16x16x128_f8f6f4 v[28:31], v[152:159], v[210:217], v[28:31], v254, v254 op_sel_hi:[0,0,0]
	v_mfma_scale_f32_16x16x128_f8f6f4 v[24:27], v[144:151], v[210:217], v[24:27], v254, v254 op_sel_hi:[0,0,0]
	v_mfma_scale_f32_16x16x128_f8f6f4 v[12:15], v[152:159], v[218:225], v[12:15], v254, v254 op_sel_hi:[0,0,0]
	v_mfma_scale_f32_16x16x128_f8f6f4 v[8:11], v[144:151], v[218:225], v[8:11], v254, v254 op_sel_hi:[0,0,0]
	s_setprio 0
	s_setprio 1
	v_mfma_scale_f32_16x16x128_f8f6f4 v[52:55], v[136:143], v[194:201], v[52:55], v254, v254 op_sel_hi:[0,0,0]
	v_mfma_scale_f32_16x16x128_f8f6f4 v[48:51], v[128:135], v[194:201], v[48:51], v254, v254 op_sel_hi:[0,0,0]
	v_mfma_scale_f32_16x16x128_f8f6f4 v[36:39], v[136:143], v[202:209], v[36:39], v254, v254 op_sel_hi:[0,0,0]
	v_mfma_scale_f32_16x16x128_f8f6f4 v[32:35], v[128:135], v[202:209], v[32:35], v254, v254 op_sel_hi:[0,0,0]
	v_mfma_scale_f32_16x16x128_f8f6f4 v[20:23], v[136:143], v[210:217], v[20:23], v254, v254 op_sel_hi:[0,0,0]
	v_mfma_scale_f32_16x16x128_f8f6f4 v[16:19], v[128:135], v[210:217], v[16:19], v254, v254 op_sel_hi:[0,0,0]
	v_mfma_scale_f32_16x16x128_f8f6f4 v[4:7], v[136:143], v[218:225], v[4:7], v254, v254 op_sel_hi:[0,0,0]
	v_mfma_scale_f32_16x16x128_f8f6f4 v[0:3], v[128:135], v[218:225], v[0:3], v254, v254 op_sel_hi:[0,0,0]
	s_setprio 0
	s_add_i32 s53, s53, 2
	s_add_u32 s28, s28, 0x100
	s_addc_u32 s29, s29, 0
	s_add_u32 s50, s50, 0x100
	s_addc_u32 s51, s51, 0
	s_cmp_gt_u32 s53, 13
	s_barrier
	s_cbranch_scc0 .LBB0_208
	s_and_b64 vcc, exec, s[14:15]
	s_cbranch_vccz .LBB0_211
	s_barrier

; #define PG8_STAGE(bufoff, gbase, voff) do { _Pragma("unroll") for (int _i = 0; _i < 2; ++_i) \
;         __builtin_amdgcn_global_load_lds((const unsigned*)((const char*)(gbase) + (voff)[_i]), (LAS unsigned*)(lds + (bufoff) + ldsw + _i * 8192), 16, 0, 0); } while (0)
; #define PG8_LDA(dst, b, h) do { _Pragma("unroll") for (int m = 0; m < 4; ++m) _Pragma("unroll") for (int k = 0; k < 2; ++k) dst[m][k] = *(const LAS bf16x8*)(lds + PG8_SA(b, h) + aoff + m * 2048 + k * 1024); } while (0)
; #define PG8_LDB(dst, b, h) do { _Pragma("unroll") for (int n = 0; n < 2; ++n) _Pragma("unroll") for (int k = 0; k < 2; ++k) dst[n][k] = *(const LAS bf16x8*)(lds + PG8_SB(b, h) + boff + n * 2048 + k * 1024); } while (0)
; #define PG8_WAIT_V(n) asm volatile("s_waitcnt vmcnt(" #n ")" ::: "memory")
; #define PG8_WAIT_L(n) asm volatile("s_waitcnt lgkmcnt(" #n ")" ::: "memory")
; #define PG8_BAR __builtin_amdgcn_s_barrier()
; #define PG8_SCHED __builtin_amdgcn_sched_barrier(0)
; template <class Epi, class Sched, bool F8 = false>
; __device__ __forceinline__ void gemm_phase(LAS unsigned char* lds, const Gemm g, const Sched& S, const Epi& E) {
;     ...
;         for (int t = 0; t < nt; t += 2) {
;             const bool last = (t == nt - 2);
;             const char* a1 = cA + (size_t)(t + 1) * kstep;
;             const char* a2 = last ? nA : cA + (size_t)(t + 2) * kstep; const char* b2 = last ? nB : cB + (size_t)(t + 2) * kstep;
;             const char* a3 = a2 + kstep; const char* b3 = b2 + kstep;
;             PG8_LDB(B0, 0, 0); PG8_LDB(B1, 0, 1); PG8_SCHED; PG8_LDA(At, 0, 0); PG8_STAGE(PG8_SA(1, 1), a1 + hstepA, voffA);
;             PG8_WAIT_V(8); PG8_WAIT_L(0); PG8_BAR; PG8_MMA(0, 0, At, B0); PG8_MMA(0, 1, At, B1); PG8_BAR; PG8_SCHED;
;             PG8_LDA(At, 0, 1); PG8_STAGE(PG8_SB(0, 0), b2, voffB); PG8_STAGE(PG8_SB(0, 1), b2 + hstepB, voffB); PG8_STAGE(PG8_SA(0, 0), a2, voffA);
;             PG8_WAIT_V(8); PG8_WAIT_L(0); PG8_BAR; PG8_MMA(1, 0, At, B0); PG8_MMA(1, 1, At, B1); PG8_BAR; PG8_SCHED;
.LBB0_356:
	ds_read_b128 v[168:171], v158
	ds_read_b128 v[172:175], v158 offset:1024
	ds_read_b128 v[176:179], v158 offset:2048
	ds_read_b128 v[180:183], v158 offset:3072
	ds_read_b128 v[184:187], v160
	ds_read_b128 v[192:195], v160 offset:1024
	ds_read_b128 v[196:199], v160 offset:2048
	ds_read_b128 v[200:203], v160 offset:3072
	s_add_u32 s8, s30, 0x100
	s_addc_u32 s9, s31, 0
	s_cmp_eq_u32 s59, 4
	s_cselect_b32 s37, s25, s9
	s_cselect_b32 s36, s24, s8
	s_cselect_b32 s35, s10, s58
	s_cselect_b32 s34, s21, s29
	s_add_i32 m0, s40, 0xc000
	ds_read_b128 v[204:207], v159
	ds_read_b128 v[208:211], v159 offset:1024
	ds_read_b128 v[212:215], v159 offset:2048
	ds_read_b128 v[216:219], v159 offset:3072
	ds_read_b128 v[220:223], v159 offset:4096
	ds_read_b128 v[224:227], v159 offset:5120
	ds_read_b128 v[228:231], v159 offset:6144
	ds_read_b128 v[232:235], v159 offset:7168
	global_load_lds_dwordx4 v144, s[30:31]
	s_add_i32 m0, s40, 0xe000
	s_nop 0
	global_load_lds_dwordx4 v146, s[30:31]
	s_waitcnt vmcnt(8)
	s_waitcnt lgkmcnt(0)
	s_barrier
	s_setprio 1
	s_waitcnt lgkmcnt(0)
	v_mfma_f32_16x16x32_bf16 v[124:127], v[168:171], v[204:207], v[124:127]
	v_mfma_f32_16x16x32_bf16 v[120:123], v[176:179], v[204:207], v[120:123]
	v_mfma_f32_16x16x32_bf16 v[108:111], v[168:171], v[212:215], v[108:111]
	v_mfma_f32_16x16x32_bf16 v[104:107], v[176:179], v[212:215], v[104:107]
	v_mfma_f32_16x16x32_bf16 v[92:95], v[168:171], v[220:223], v[92:95]
	v_mfma_f32_16x16x32_bf16 v[88:91], v[176:179], v[220:223], v[88:91]
	v_mfma_f32_16x16x32_bf16 v[76:79], v[168:171], v[228:231], v[76:79]
	v_mfma_f32_16x16x32_bf16 v[72:75], v[176:179], v[228:231], v[72:75]
	v_mfma_f32_16x16x32_bf16 v[124:127], v[172:175], v[208:211], v[124:127]
	v_mfma_f32_16x16x32_bf16 v[120:123], v[180:183], v[208:211], v[120:123]
	v_mfma_f32_16x16x32_bf16 v[108:111], v[172:175], v[216:219], v[108:111]
	v_mfma_f32_16x16x32_bf16 v[104:107], v[180:183], v[216:219], v[104:107]
	v_mfma_f32_16x16x32_bf16 v[92:95], v[172:175], v[224:227], v[92:95]
	v_mfma_f32_16x16x32_bf16 v[88:91], v[180:183], v[224:227], v[88:91]
	v_mfma_f32_16x16x32_bf16 v[76:79], v[172:175], v[232:235], v[76:79]
	v_mfma_f32_16x16x32_bf16 v[72:75], v[180:183], v[232:235], v[72:75]
	s_setprio 0
	s_setprio 1
	v_mfma_f32_16x16x32_bf16 v[116:119], v[184:187], v[204:207], v[116:119]
	v_mfma_f32_16x16x32_bf16 v[112:115], v[196:199], v[204:207], v[112:115]
	v_mfma_f32_16x16x32_bf16 v[100:103], v[184:187], v[212:215], v[100:103]
	v_mfma_f32_16x16x32_bf16 v[96:99], v[196:199], v[212:215], v[96:99]
	v_mfma_f32_16x16x32_bf16 v[84:87], v[184:187], v[220:223], v[84:87]
	v_mfma_f32_16x16x32_bf16 v[80:83], v[196:199], v[220:223], v[80:83]
	v_mfma_f32_16x16x32_bf16 v[68:71], v[184:187], v[228:231], v[68:71]
	v_mfma_f32_16x16x32_bf16 v[64:67], v[196:199], v[228:231], v[64:67]
	v_mfma_f32_16x16x32_bf16 v[116:119], v[192:195], v[208:211], v[116:119]
	v_mfma_f32_16x16x32_bf16 v[112:115], v[200:203], v[208:211], v[112:115]
	v_mfma_f32_16x16x32_bf16 v[100:103], v[192:195], v[216:219], v[100:103]
	v_mfma_f32_16x16x32_bf16 v[96:99], v[200:203], v[216:219], v[96:99]
	v_mfma_f32_16x16x32_bf16 v[84:87], v[192:195], v[224:227], v[84:87]
	v_mfma_f32_16x16x32_bf16 v[80:83], v[200:203], v[224:227], v[80:83]
	v_mfma_f32_16x16x32_bf16 v[68:71], v[192:195], v[232:235], v[68:71]
	v_mfma_f32_16x16x32_bf16 v[64:67], v[200:203], v[232:235], v[64:67]
	s_setprio 0
	s_barrier
	s_add_i32 s30, s50, s39
	v_lshl_add_u64 v[152:153], s[34:35], 0, v[130:131]
	s_mov_b32 m0, s30
	ds_read_b128 v[204:207], v159 offset:16384
	ds_read_b128 v[208:211], v159 offset:17408
	ds_read_b128 v[212:215], v159 offset:18432
	ds_read_b128 v[216:219], v159 offset:19456
	ds_read_b128 v[220:223], v159 offset:20480
	ds_read_b128 v[224:227], v159 offset:21504
	ds_read_b128 v[228:231], v159 offset:22528
	ds_read_b128 v[232:235], v159 offset:23552
	global_load_lds_dwordx4 v[152:153], off
	s_add_i32 m0, s30, 0x2000
	s_add_u32 s30, s34, 0x20000
	v_lshl_add_u64 v[188:189], s[34:35], 0, v[134:135]
	s_addc_u32 s31, s35, 0
	s_add_i32 s72, s51, s39
	global_load_lds_dwordx4 v[188:189], off
	s_mov_b32 m0, s72
	v_lshl_add_u64 v[238:239], s[36:37], 0, v[132:133]
	global_load_lds_dwordx4 v130, s[30:31]
	s_add_i32 m0, s72, 0x2000
	s_nop 0
	global_load_lds_dwordx4 v134, s[30:31]
	v_lshl_add_u64 v[236:237], s[36:37], 0, v[128:129]
	s_mov_b32 m0, s40
	s_nop 0
	global_load_lds_dwordx4 v[236:237], off
	s_mov_b32 m0, s41
	s_nop 0
	global_load_lds_dwordx4 v[238:239], off
	s_waitcnt vmcnt(8)
	s_waitcnt lgkmcnt(0)
	s_barrier
; #define PG8_STAGE(bufoff, gbase, voff) do { _Pragma("unroll") for (int _i = 0; _i < 2; ++_i) \
;         __builtin_amdgcn_global_load_lds((const unsigned*)((const char*)(gbase) + (voff)[_i]), (LAS unsigned*)(lds + (bufoff) + ldsw + _i * 8192), 16, 0, 0); } while (0)
; #define PG8_LDA(dst, b, h) do { _Pragma("unroll") for (int m = 0; m < 4; ++m) _Pragma("unroll") for (int k = 0; k < 2; ++k) dst[m][k] = *(const LAS bf16x8*)(lds + PG8_SA(b, h) + aoff + m * 2048 + k * 1024); } while (0)
; #define PG8_LDB(dst, b, h) do { _Pragma("unroll") for (int n = 0; n < 2; ++n) _Pragma("unroll") for (int k = 0; k < 2; ++k) dst[n][k] = *(const LAS bf16x8*)(lds + PG8_SB(b, h) + boff + n * 2048 + k * 1024); } while (0)
; #define PG8_WAIT_V(n) asm volatile("s_waitcnt vmcnt(" #n ")" ::: "memory")
; #define PG8_WAIT_L(n) asm volatile("s_waitcnt lgkmcnt(" #n ")" ::: "memory")
; #define PG8_BAR __builtin_amdgcn_s_barrier()
; #define PG8_SCHED __builtin_amdgcn_sched_barrier(0)
; template <class Epi, class Sched, bool F8 = false>
; __device__ __forceinline__ void gemm_phase(LAS unsigned char* lds, const Gemm g, const Sched& S, const Epi& E) {
;     ...
;             PG8_WAIT_V(8); PG8_WAIT_L(0); PG8_BAR; PG8_MMA(1, 0, At, B0); PG8_MMA(1, 1, At, B1); PG8_BAR; PG8_SCHED;
;             PG8_LDB(B0, 1, 0); PG8_LDB(B1, 1, 1); PG8_SCHED; PG8_LDA(At, 1, 0); PG8_STAGE(PG8_SA(0, 1), a2 + hstepA, voffA);
;             PG8_WAIT_V(8); PG8_WAIT_L(0); PG8_BAR; PG8_MMA(0, 0, At, B0); PG8_MMA(0, 1, At, B1); PG8_BAR; PG8_SCHED;
	s_setprio 1
	s_waitcnt lgkmcnt(0)
	v_mfma_f32_16x16x32_bf16 v[60:63], v[168:171], v[204:207], v[60:63]
	v_mfma_f32_16x16x32_bf16 v[56:59], v[176:179], v[204:207], v[56:59]
	v_mfma_f32_16x16x32_bf16 v[44:47], v[168:171], v[212:215], v[44:47]
	v_mfma_f32_16x16x32_bf16 v[40:43], v[176:179], v[212:215], v[40:43]
	v_mfma_f32_16x16x32_bf16 v[28:31], v[168:171], v[220:223], v[28:31]
	v_mfma_f32_16x16x32_bf16 v[24:27], v[176:179], v[220:223], v[24:27]
	v_mfma_f32_16x16x32_bf16 v[12:15], v[168:171], v[228:231], v[12:15]
	v_mfma_f32_16x16x32_bf16 v[8:11], v[176:179], v[228:231], v[8:11]
	v_mfma_f32_16x16x32_bf16 v[60:63], v[172:175], v[208:211], v[60:63]
	v_mfma_f32_16x16x32_bf16 v[56:59], v[180:183], v[208:211], v[56:59]
	v_mfma_f32_16x16x32_bf16 v[44:47], v[172:175], v[216:219], v[44:47]
	v_mfma_f32_16x16x32_bf16 v[40:43], v[180:183], v[216:219], v[40:43]
	v_mfma_f32_16x16x32_bf16 v[28:31], v[172:175], v[224:227], v[28:31]
	v_mfma_f32_16x16x32_bf16 v[24:27], v[180:183], v[224:227], v[24:27]
	v_mfma_f32_16x16x32_bf16 v[12:15], v[172:175], v[232:235], v[12:15]
	v_mfma_f32_16x16x32_bf16 v[8:11], v[180:183], v[232:235], v[8:11]
	s_setprio 0
	s_setprio 1
	v_mfma_f32_16x16x32_bf16 v[52:55], v[184:187], v[204:207], v[52:55]
	v_mfma_f32_16x16x32_bf16 v[48:51], v[196:199], v[204:207], v[48:51]
	v_mfma_f32_16x16x32_bf16 v[36:39], v[184:187], v[212:215], v[36:39]
	v_mfma_f32_16x16x32_bf16 v[32:35], v[196:199], v[212:215], v[32:35]
	v_mfma_f32_16x16x32_bf16 v[20:23], v[184:187], v[220:223], v[20:23]
	v_mfma_f32_16x16x32_bf16 v[16:19], v[196:199], v[220:223], v[16:19]
	v_mfma_f32_16x16x32_bf16 v[4:7], v[184:187], v[228:231], v[4:7]
	v_mfma_f32_16x16x32_bf16 v[0:3], v[196:199], v[228:231], v[0:3]
	v_mfma_f32_16x16x32_bf16 v[52:55], v[192:195], v[208:211], v[52:55]
	v_mfma_f32_16x16x32_bf16 v[48:51], v[200:203], v[208:211], v[48:51]
	v_mfma_f32_16x16x32_bf16 v[36:39], v[192:195], v[216:219], v[36:39]
	v_mfma_f32_16x16x32_bf16 v[32:35], v[200:203], v[216:219], v[32:35]
	v_mfma_f32_16x16x32_bf16 v[20:23], v[192:195], v[224:227], v[20:23]
	v_mfma_f32_16x16x32_bf16 v[16:19], v[200:203], v[224:227], v[16:19]
	v_mfma_f32_16x16x32_bf16 v[4:7], v[192:195], v[232:235], v[4:7]
	v_mfma_f32_16x16x32_bf16 v[0:3], v[200:203], v[232:235], v[0:3]
	s_setprio 0
	s_barrier
	s_add_i32 s72, 0, 0x18000
	v_add_u32_e32 v154, s72, v156
	s_add_i32 s73, 0, 0x1c000
	ds_read_b128 v[168:171], v154
	ds_read_b128 v[172:175], v154 offset:1024
	ds_read_b128 v[176:179], v154 offset:2048
	ds_read_b128 v[180:183], v154 offset:3072
	v_add_u32_e32 v154, s73, v156
	ds_read_b128 v[184:187], v154
	ds_read_b128 v[192:195], v154 offset:1024
	ds_read_b128 v[196:199], v154 offset:2048
	ds_read_b128 v[200:203], v154 offset:3072
	s_add_u32 s30, s36, 0xc0000
	s_addc_u32 s31, s37, 0
	s_mov_b32 m0, s42
	ds_read_b128 v[204:207], v159 offset:32768
	ds_read_b128 v[208:211], v159 offset:33792
	ds_read_b128 v[212:215], v159 offset:34816
	ds_read_b128 v[216:219], v159 offset:35840
	ds_read_b128 v[220:223], v159 offset:36864
	ds_read_b128 v[224:227], v159 offset:37888
	ds_read_b128 v[228:231], v159 offset:38912
	ds_read_b128 v[232:235], v159 offset:39936
	global_load_lds_dwordx4 v128, s[30:31]
	s_mov_b32 m0, s43
	s_nop 0
	global_load_lds_dwordx4 v132, s[30:31]
	s_waitcnt vmcnt(8)
	s_waitcnt lgkmcnt(0)
	s_barrier
	s_setprio 1
	s_waitcnt lgkmcnt(0)
	v_mfma_f32_16x16x32_bf16 v[124:127], v[168:171], v[204:207], v[124:127]
	v_mfma_f32_16x16x32_bf16 v[120:123], v[176:179], v[204:207], v[120:123]
	v_mfma_f32_16x16x32_bf16 v[108:111], v[168:171], v[212:215], v[108:111]
	v_mfma_f32_16x16x32_bf16 v[104:107], v[176:179], v[212:215], v[104:107]
	v_mfma_f32_16x16x32_bf16 v[92:95], v[168:171], v[220:223], v[92:95]
	v_mfma_f32_16x16x32_bf16 v[88:91], v[176:179], v[220:223], v[88:91]
	v_mfma_f32_16x16x32_bf16 v[76:79], v[168:171], v[228:231], v[76:79]
	v_mfma_f32_16x16x32_bf16 v[72:75], v[176:179], v[228:231], v[72:75]
	v_mfma_f32_16x16x32_bf16 v[124:127], v[172:175], v[208:211], v[124:127]
	v_mfma_f32_16x16x32_bf16 v[120:123], v[180:183], v[208:211], v[120:123]
	v_mfma_f32_16x16x32_bf16 v[108:111], v[172:175], v[216:219], v[108:111]
	v_mfma_f32_16x16x32_bf16 v[104:107], v[180:183], v[216:219], v[104:107]
	v_mfma_f32_16x16x32_bf16 v[92:95], v[172:175], v[224:227], v[92:95]
	v_mfma_f32_16x16x32_bf16 v[88:91], v[180:183], v[224:227], v[88:91]
	v_mfma_f32_16x16x32_bf16 v[76:79], v[172:175], v[232:235], v[76:79]
	v_mfma_f32_16x16x32_bf16 v[72:75], v[180:183], v[232:235], v[72:75]
	s_setprio 0
	s_setprio 1
	v_mfma_f32_16x16x32_bf16 v[116:119], v[184:187], v[204:207], v[116:119]
	v_mfma_f32_16x16x32_bf16 v[112:115], v[196:199], v[204:207], v[112:115]
	v_mfma_f32_16x16x32_bf16 v[100:103], v[184:187], v[212:215], v[100:103]
	v_mfma_f32_16x16x32_bf16 v[96:99], v[196:199], v[212:215], v[96:99]
	v_mfma_f32_16x16x32_bf16 v[84:87], v[184:187], v[220:223], v[84:87]
	v_mfma_f32_16x16x32_bf16 v[80:83], v[196:199], v[220:223], v[80:83]
	v_mfma_f32_16x16x32_bf16 v[68:71], v[184:187], v[228:231], v[68:71]
	v_mfma_f32_16x16x32_bf16 v[64:67], v[196:199], v[228:231], v[64:67]
	v_mfma_f32_16x16x32_bf16 v[116:119], v[192:195], v[208:211], v[116:119]
	v_mfma_f32_16x16x32_bf16 v[112:115], v[200:203], v[208:211], v[112:115]
	v_mfma_f32_16x16x32_bf16 v[100:103], v[192:195], v[216:219], v[100:103]
	v_mfma_f32_16x16x32_bf16 v[96:99], v[200:203], v[216:219], v[96:99]
	v_mfma_f32_16x16x32_bf16 v[84:87], v[192:195], v[224:227], v[84:87]
	v_mfma_f32_16x16x32_bf16 v[80:83], v[200:203], v[224:227], v[80:83]
	v_mfma_f32_16x16x32_bf16 v[68:71], v[192:195], v[232:235], v[68:71]
	v_mfma_f32_16x16x32_bf16 v[64:67], v[200:203], v[232:235], v[64:67]
	s_setprio 0
	s_barrier
; #define PG8_STAGE(bufoff, gbase, voff) do { _Pragma("unroll") for (int _i = 0; _i < 2; ++_i) \
;         __builtin_amdgcn_global_load_lds((const unsigned*)((const char*)(gbase) + (voff)[_i]), (LAS unsigned*)(lds + (bufoff) + ldsw + _i * 8192), 16, 0, 0); } while (0)
; #define PG8_LDA(dst, b, h) do { _Pragma("unroll") for (int m = 0; m < 4; ++m) _Pragma("unroll") for (int k = 0; k < 2; ++k) dst[m][k] = *(const LAS bf16x8*)(lds + PG8_SA(b, h) + aoff + m * 2048 + k * 1024); } while (0)
; #define PG8_WAIT_V(n) asm volatile("s_waitcnt vmcnt(" #n ")" ::: "memory")
; #define PG8_WAIT_L(n) asm volatile("s_waitcnt lgkmcnt(" #n ")" ::: "memory")
; #define PG8_BAR __builtin_amdgcn_s_barrier()
; #define PG8_SCHED __builtin_amdgcn_sched_barrier(0)
; template <class Epi, class Sched, bool F8 = false>
; __device__ __forceinline__ void gemm_phase(LAS unsigned char* lds, const Gemm g, const Sched& S, const Epi& E) {
;     ...
;             PG8_LDA(At, 1, 1); PG8_STAGE(PG8_SB(1, 0), b3, voffB); PG8_STAGE(PG8_SB(1, 1), b3 + hstepB, voffB); PG8_STAGE(PG8_SA(1, 0), a3, voffA);
;             PG8_WAIT_V(8); PG8_WAIT_L(0); PG8_BAR; PG8_MMA(1, 0, At, B0); PG8_MMA(1, 1, At, B1); PG8_BAR; PG8_SCHED;
;         }
	s_add_i32 s30, s72, s39
	s_add_i32 m0, s30, 0xffffff80
	ds_read_b128 v[204:207], v159 offset:49152
	ds_read_b128 v[208:211], v159 offset:50176
	ds_read_b128 v[212:215], v159 offset:51200
	ds_read_b128 v[216:219], v159 offset:52224
	ds_read_b128 v[220:223], v159 offset:53248
	ds_read_b128 v[224:227], v159 offset:54272
	ds_read_b128 v[228:231], v159 offset:55296
	ds_read_b128 v[232:235], v159 offset:56320
	global_load_lds_dwordx4 v[152:153], off offset:128
	s_add_i32 m0, s30, 0x1f80
	s_add_u32 s30, s34, 0x20080
	s_addc_u32 s31, s35, 0
	s_add_i32 s34, s73, s39
	global_load_lds_dwordx4 v[188:189], off offset:128
	s_mov_b32 m0, s34
	s_nop 0
	global_load_lds_dwordx4 v130, s[30:31]
	s_add_i32 m0, s34, 0x2000
	s_nop 0
	global_load_lds_dwordx4 v134, s[30:31]
	s_add_i32 m0, s45, 0xffffff80
	s_nop 0
	global_load_lds_dwordx4 v[236:237], off offset:128
	s_add_i32 m0, s47, 0xffffff80
	s_nop 0
	global_load_lds_dwordx4 v[238:239], off offset:128
	s_waitcnt vmcnt(8)
	s_waitcnt lgkmcnt(0)
	s_barrier
	s_setprio 1
	s_waitcnt lgkmcnt(0)
	v_mfma_f32_16x16x32_bf16 v[60:63], v[168:171], v[204:207], v[60:63]
	v_mfma_f32_16x16x32_bf16 v[56:59], v[176:179], v[204:207], v[56:59]
	v_mfma_f32_16x16x32_bf16 v[44:47], v[168:171], v[212:215], v[44:47]
	v_mfma_f32_16x16x32_bf16 v[40:43], v[176:179], v[212:215], v[40:43]
	v_mfma_f32_16x16x32_bf16 v[28:31], v[168:171], v[220:223], v[28:31]
	v_mfma_f32_16x16x32_bf16 v[24:27], v[176:179], v[220:223], v[24:27]
	v_mfma_f32_16x16x32_bf16 v[12:15], v[168:171], v[228:231], v[12:15]
	v_mfma_f32_16x16x32_bf16 v[8:11], v[176:179], v[228:231], v[8:11]
	v_mfma_f32_16x16x32_bf16 v[60:63], v[172:175], v[208:211], v[60:63]
	v_mfma_f32_16x16x32_bf16 v[56:59], v[180:183], v[208:211], v[56:59]
	v_mfma_f32_16x16x32_bf16 v[44:47], v[172:175], v[216:219], v[44:47]
	v_mfma_f32_16x16x32_bf16 v[40:43], v[180:183], v[216:219], v[40:43]
	v_mfma_f32_16x16x32_bf16 v[28:31], v[172:175], v[224:227], v[28:31]
	v_mfma_f32_16x16x32_bf16 v[24:27], v[180:183], v[224:227], v[24:27]
	v_mfma_f32_16x16x32_bf16 v[12:15], v[172:175], v[232:235], v[12:15]
	v_mfma_f32_16x16x32_bf16 v[8:11], v[180:183], v[232:235], v[8:11]
	s_setprio 0
	s_setprio 1
	v_mfma_f32_16x16x32_bf16 v[52:55], v[184:187], v[204:207], v[52:55]
	v_mfma_f32_16x16x32_bf16 v[48:51], v[196:199], v[204:207], v[48:51]
	v_mfma_f32_16x16x32_bf16 v[36:39], v[184:187], v[212:215], v[36:39]
	v_mfma_f32_16x16x32_bf16 v[32:35], v[196:199], v[212:215], v[32:35]
	v_mfma_f32_16x16x32_bf16 v[20:23], v[184:187], v[220:223], v[20:23]
	v_mfma_f32_16x16x32_bf16 v[16:19], v[196:199], v[220:223], v[16:19]
	v_mfma_f32_16x16x32_bf16 v[4:7], v[184:187], v[228:231], v[4:7]
	v_mfma_f32_16x16x32_bf16 v[0:3], v[196:199], v[228:231], v[0:3]
	v_mfma_f32_16x16x32_bf16 v[52:55], v[192:195], v[208:211], v[52:55]
	v_mfma_f32_16x16x32_bf16 v[48:51], v[200:203], v[208:211], v[48:51]
	v_mfma_f32_16x16x32_bf16 v[36:39], v[192:195], v[216:219], v[36:39]
	v_mfma_f32_16x16x32_bf16 v[32:35], v[200:203], v[216:219], v[32:35]
	v_mfma_f32_16x16x32_bf16 v[20:23], v[192:195], v[224:227], v[20:23]
	v_mfma_f32_16x16x32_bf16 v[16:19], v[200:203], v[224:227], v[16:19]
	v_mfma_f32_16x16x32_bf16 v[4:7], v[192:195], v[232:235], v[4:7]
	v_mfma_f32_16x16x32_bf16 v[0:3], v[200:203], v[232:235], v[0:3]
	s_setprio 0
	s_add_i32 s59, s59, 2
	s_add_u32 s29, s29, 0x100
	s_addc_u32 s58, s58, 0
	s_cmp_gt_u32 s59, 5
	s_mov_b64 s[30:31], s[8:9]
	s_barrier
	s_cbranch_scc0 .LBB0_356
	s_and_b64 vcc, exec, s[18:19]
	s_cbranch_vccz .LBB0_359
	s_barrier

; #define PG8_STAGE(bufoff, gbase, voff) do { _Pragma("unroll") for (int _i = 0; _i < 2; ++_i) \
;         __builtin_amdgcn_global_load_lds((const unsigned*)((const char*)(gbase) + (voff)[_i]), (LAS unsigned*)(lds + (bufoff) + ldsw + _i * 8192), 16, 0, 0); } while (0)
; #define PG8_LDA(dst, b, h) do { _Pragma("unroll") for (int m = 0; m < 4; ++m) _Pragma("unroll") for (int k = 0; k < 2; ++k) dst[m][k] = *(const LAS bf16x8*)(lds + PG8_SA(b, h) + aoff + m * 2048 + k * 1024); } while (0)
; #define PG8_LDB(dst, b, h) do { _Pragma("unroll") for (int n = 0; n < 2; ++n) _Pragma("unroll") for (int k = 0; k < 2; ++k) dst[n][k] = *(const LAS bf16x8*)(lds + PG8_SB(b, h) + boff + n * 2048 + k * 1024); } while (0)
; #define PG8_WAIT_V(n) asm volatile("s_waitcnt vmcnt(" #n ")" ::: "memory")
; #define PG8_WAIT_L(n) asm volatile("s_waitcnt lgkmcnt(" #n ")" ::: "memory")
; #define PG8_BAR __builtin_amdgcn_s_barrier()
; #define PG8_SCHED __builtin_amdgcn_sched_barrier(0)
; template <class Epi, class Sched, bool F8 = false>
; __device__ __forceinline__ void gemm_phase(LAS unsigned char* lds, const Gemm g, const Sched& S, const Epi& E) {
;     ...
;         for (int t = 0; t < nt; t += 2) {
;             const bool last = (t == nt - 2);
;             const char* a1 = cA + (size_t)(t + 1) * kstep;
;             const char* a2 = last ? nA : cA + (size_t)(t + 2) * kstep; const char* b2 = last ? nB : cB + (size_t)(t + 2) * kstep;
;             const char* a3 = a2 + kstep; const char* b3 = b2 + kstep;
;             PG8_LDB(B0, 0, 0); PG8_LDB(B1, 0, 1); PG8_SCHED; PG8_LDA(At, 0, 0); PG8_STAGE(PG8_SA(1, 1), a1 + hstepA, voffA);
;             PG8_WAIT_V(8); PG8_WAIT_L(0); PG8_BAR; PG8_MMA(0, 0, At, B0); PG8_MMA(0, 1, At, B1); PG8_BAR; PG8_SCHED;
;             PG8_LDA(At, 0, 1); PG8_STAGE(PG8_SB(0, 0), b2, voffB); PG8_STAGE(PG8_SB(0, 1), b2 + hstepB, voffB); PG8_STAGE(PG8_SA(0, 0), a2, voffA);
;             PG8_WAIT_V(8); PG8_WAIT_L(0); PG8_BAR; PG8_MMA(1, 0, At, B0); PG8_MMA(1, 1, At, B1); PG8_BAR; PG8_SCHED;
.LBB0_753:
	v_add_u32_e32 v140, s48, v197
	v_add_u32_e32 v156, s91, v197
	ds_read_b128 v[128:131], v140
	ds_read_b128 v[132:135], v140 offset:1024
	ds_read_b128 v[136:139], v140 offset:2048
	ds_read_b128 v[140:143], v140 offset:3072
	ds_read_b128 v[144:147], v156
	ds_read_b128 v[148:151], v156 offset:1024
	ds_read_b128 v[152:155], v156 offset:2048
	ds_read_b128 v[156:159], v156 offset:3072
	s_add_i32 s80, s34, 2
	s_add_u32 s35, s30, 0xfff80080
	s_addc_u32 s36, s31, -1
	s_cmp_eq_u32 s77, s34
	s_cselect_b32 s34, s76, s78
	s_cselect_b32 s37, s25, s36
	s_cselect_b32 s36, s75, s35
	s_cselect_b32 s35, s21, s79
	s_add_i32 m0, s40, 0xc000
	ds_read_b128 v[160:163], v199
	ds_read_b128 v[164:167], v199 offset:1024
	ds_read_b128 v[168:171], v199 offset:2048
	ds_read_b128 v[172:175], v199 offset:3072
	ds_read_b128 v[200:203], v199 offset:4096
	ds_read_b128 v[204:207], v199 offset:5120
	ds_read_b128 v[208:211], v199 offset:6144
	ds_read_b128 v[212:215], v199 offset:7168
	global_load_lds_dwordx4 v186, s[30:31]
	s_add_i32 m0, s40, 0xe000
	s_nop 0
	global_load_lds_dwordx4 v188, s[30:31]
	s_waitcnt vmcnt(8)
	s_waitcnt lgkmcnt(0)
	s_barrier
	s_setprio 1
	s_waitcnt lgkmcnt(0)
	v_mfma_f32_16x16x32_bf16 v[124:127], v[128:131], v[160:163], v[124:127]
	v_mfma_f32_16x16x32_bf16 v[120:123], v[136:139], v[160:163], v[120:123]
	v_mfma_f32_16x16x32_bf16 v[116:119], v[128:131], v[168:171], v[116:119]
	v_mfma_f32_16x16x32_bf16 v[112:115], v[136:139], v[168:171], v[112:115]
	v_mfma_f32_16x16x32_bf16 v[108:111], v[128:131], v[200:203], v[108:111]
	v_mfma_f32_16x16x32_bf16 v[104:107], v[136:139], v[200:203], v[104:107]
	v_mfma_f32_16x16x32_bf16 v[100:103], v[128:131], v[208:211], v[100:103]
	v_mfma_f32_16x16x32_bf16 v[96:99], v[136:139], v[208:211], v[96:99]
	v_mfma_f32_16x16x32_bf16 v[124:127], v[132:135], v[164:167], v[124:127]
	v_mfma_f32_16x16x32_bf16 v[120:123], v[140:143], v[164:167], v[120:123]
	v_mfma_f32_16x16x32_bf16 v[116:119], v[132:135], v[172:175], v[116:119]
	v_mfma_f32_16x16x32_bf16 v[112:115], v[140:143], v[172:175], v[112:115]
	v_mfma_f32_16x16x32_bf16 v[108:111], v[132:135], v[204:207], v[108:111]
	v_mfma_f32_16x16x32_bf16 v[104:107], v[140:143], v[204:207], v[104:107]
	v_mfma_f32_16x16x32_bf16 v[100:103], v[132:135], v[212:215], v[100:103]
	v_mfma_f32_16x16x32_bf16 v[96:99], v[140:143], v[212:215], v[96:99]
	s_setprio 0
	s_setprio 1
	v_mfma_f32_16x16x32_bf16 v[92:95], v[144:147], v[160:163], v[92:95]
	v_mfma_f32_16x16x32_bf16 v[88:91], v[152:155], v[160:163], v[88:91]
	v_mfma_f32_16x16x32_bf16 v[84:87], v[144:147], v[168:171], v[84:87]
	v_mfma_f32_16x16x32_bf16 v[80:83], v[152:155], v[168:171], v[80:83]
	v_mfma_f32_16x16x32_bf16 v[76:79], v[144:147], v[200:203], v[76:79]
	v_mfma_f32_16x16x32_bf16 v[72:75], v[152:155], v[200:203], v[72:75]
	v_mfma_f32_16x16x32_bf16 v[68:71], v[144:147], v[208:211], v[68:71]
	v_mfma_f32_16x16x32_bf16 v[64:67], v[152:155], v[208:211], v[64:67]
	v_mfma_f32_16x16x32_bf16 v[92:95], v[148:151], v[164:167], v[92:95]
	v_mfma_f32_16x16x32_bf16 v[88:91], v[156:159], v[164:167], v[88:91]
	v_mfma_f32_16x16x32_bf16 v[84:87], v[148:151], v[172:175], v[84:87]
	v_mfma_f32_16x16x32_bf16 v[80:83], v[156:159], v[172:175], v[80:83]
	v_mfma_f32_16x16x32_bf16 v[76:79], v[148:151], v[204:207], v[76:79]
	v_mfma_f32_16x16x32_bf16 v[72:75], v[156:159], v[204:207], v[72:75]
	v_mfma_f32_16x16x32_bf16 v[68:71], v[148:151], v[212:215], v[68:71]
	v_mfma_f32_16x16x32_bf16 v[64:67], v[156:159], v[212:215], v[64:67]
	s_setprio 0
	s_barrier
	s_add_i32 s81, s48, s38
	v_lshl_add_u64 v[216:217], s[34:35], 0, v[180:181]
	s_mov_b32 m0, s81
	ds_read_b128 v[160:163], v199 offset:16384
	ds_read_b128 v[164:167], v199 offset:17408
	ds_read_b128 v[168:171], v199 offset:18432
	ds_read_b128 v[172:175], v199 offset:19456
	ds_read_b128 v[200:203], v199 offset:20480
	ds_read_b128 v[204:207], v199 offset:21504
	ds_read_b128 v[208:211], v199 offset:22528
	ds_read_b128 v[212:215], v199 offset:23552
	global_load_lds_dwordx4 v[216:217], off
	s_add_i32 m0, s81, 0x2000
	s_add_u32 s82, s34, 0x80000
	v_lshl_add_u64 v[218:219], s[34:35], 0, v[176:177]
	s_addc_u32 s83, s35, 0
	s_add_i32 s81, s91, s38
	global_load_lds_dwordx4 v[218:219], off
	s_mov_b32 m0, s81
	v_lshl_add_u64 v[222:223], s[36:37], 0, v[178:179]
	global_load_lds_dwordx4 v180, s[82:83]
	s_add_i32 m0, s81, 0x2000
	s_nop 0
	global_load_lds_dwordx4 v176, s[82:83]
	v_lshl_add_u64 v[220:221], s[36:37], 0, v[182:183]
	s_mov_b32 m0, s40
	s_nop 0
	global_load_lds_dwordx4 v[220:221], off
	s_mov_b32 m0, s41
	s_nop 0
	global_load_lds_dwordx4 v[222:223], off
	s_waitcnt vmcnt(8)
	s_waitcnt lgkmcnt(0)
	s_barrier
; #define PG8_STAGE(bufoff, gbase, voff) do { _Pragma("unroll") for (int _i = 0; _i < 2; ++_i) \
;         __builtin_amdgcn_global_load_lds((const unsigned*)((const char*)(gbase) + (voff)[_i]), (LAS unsigned*)(lds + (bufoff) + ldsw + _i * 8192), 16, 0, 0); } while (0)
; #define PG8_LDA(dst, b, h) do { _Pragma("unroll") for (int m = 0; m < 4; ++m) _Pragma("unroll") for (int k = 0; k < 2; ++k) dst[m][k] = *(const LAS bf16x8*)(lds + PG8_SA(b, h) + aoff + m * 2048 + k * 1024); } while (0)
; #define PG8_LDB(dst, b, h) do { _Pragma("unroll") for (int n = 0; n < 2; ++n) _Pragma("unroll") for (int k = 0; k < 2; ++k) dst[n][k] = *(const LAS bf16x8*)(lds + PG8_SB(b, h) + boff + n * 2048 + k * 1024); } while (0)
; #define PG8_WAIT_V(n) asm volatile("s_waitcnt vmcnt(" #n ")" ::: "memory")
; #define PG8_WAIT_L(n) asm volatile("s_waitcnt lgkmcnt(" #n ")" ::: "memory")
; #define PG8_BAR __builtin_amdgcn_s_barrier()
; #define PG8_SCHED __builtin_amdgcn_sched_barrier(0)
; template <class Epi, class Sched, bool F8 = false>
; __device__ __forceinline__ void gemm_phase(LAS unsigned char* lds, const Gemm g, const Sched& S, const Epi& E) {
;     ...
;             PG8_WAIT_V(8); PG8_WAIT_L(0); PG8_BAR; PG8_MMA(1, 0, At, B0); PG8_MMA(1, 1, At, B1); PG8_BAR; PG8_SCHED;
;             PG8_LDB(B0, 1, 0); PG8_LDB(B1, 1, 1); PG8_SCHED; PG8_LDA(At, 1, 0); PG8_STAGE(PG8_SA(0, 1), a2 + hstepA, voffA);
;             PG8_WAIT_V(8); PG8_WAIT_L(0); PG8_BAR; PG8_MMA(0, 0, At, B0); PG8_MMA(0, 1, At, B1); PG8_BAR; PG8_SCHED;
	s_setprio 1
	s_waitcnt lgkmcnt(0)
	v_mfma_f32_16x16x32_bf16 v[60:63], v[128:131], v[160:163], v[60:63]
	v_mfma_f32_16x16x32_bf16 v[56:59], v[136:139], v[160:163], v[56:59]
	v_mfma_f32_16x16x32_bf16 v[52:55], v[128:131], v[168:171], v[52:55]
	v_mfma_f32_16x16x32_bf16 v[48:51], v[136:139], v[168:171], v[48:51]
	v_mfma_f32_16x16x32_bf16 v[44:47], v[128:131], v[200:203], v[44:47]
	v_mfma_f32_16x16x32_bf16 v[40:43], v[136:139], v[200:203], v[40:43]
	v_mfma_f32_16x16x32_bf16 v[36:39], v[128:131], v[208:211], v[36:39]
	v_mfma_f32_16x16x32_bf16 v[32:35], v[136:139], v[208:211], v[32:35]
	v_mfma_f32_16x16x32_bf16 v[60:63], v[132:135], v[164:167], v[60:63]
	v_mfma_f32_16x16x32_bf16 v[56:59], v[140:143], v[164:167], v[56:59]
	v_mfma_f32_16x16x32_bf16 v[52:55], v[132:135], v[172:175], v[52:55]
	v_mfma_f32_16x16x32_bf16 v[48:51], v[140:143], v[172:175], v[48:51]
	v_mfma_f32_16x16x32_bf16 v[44:47], v[132:135], v[204:207], v[44:47]
	v_mfma_f32_16x16x32_bf16 v[40:43], v[140:143], v[204:207], v[40:43]
	v_mfma_f32_16x16x32_bf16 v[36:39], v[132:135], v[212:215], v[36:39]
	v_mfma_f32_16x16x32_bf16 v[32:35], v[140:143], v[212:215], v[32:35]
	s_setprio 0
	s_setprio 1
	v_mfma_f32_16x16x32_bf16 v[28:31], v[144:147], v[160:163], v[28:31]
	v_mfma_f32_16x16x32_bf16 v[24:27], v[152:155], v[160:163], v[24:27]
	v_mfma_f32_16x16x32_bf16 v[20:23], v[144:147], v[168:171], v[20:23]
	v_mfma_f32_16x16x32_bf16 v[16:19], v[152:155], v[168:171], v[16:19]
	v_mfma_f32_16x16x32_bf16 v[12:15], v[144:147], v[200:203], v[12:15]
	v_mfma_f32_16x16x32_bf16 v[8:11], v[152:155], v[200:203], v[8:11]
	v_mfma_f32_16x16x32_bf16 v[4:7], v[144:147], v[208:211], v[4:7]
	v_mfma_f32_16x16x32_bf16 v[0:3], v[152:155], v[208:211], v[0:3]
	v_mfma_f32_16x16x32_bf16 v[28:31], v[148:151], v[164:167], v[28:31]
	v_mfma_f32_16x16x32_bf16 v[24:27], v[156:159], v[164:167], v[24:27]
	v_mfma_f32_16x16x32_bf16 v[20:23], v[148:151], v[172:175], v[20:23]
	v_mfma_f32_16x16x32_bf16 v[16:19], v[156:159], v[172:175], v[16:19]
	v_mfma_f32_16x16x32_bf16 v[12:15], v[148:151], v[204:207], v[12:15]
	v_mfma_f32_16x16x32_bf16 v[8:11], v[156:159], v[204:207], v[8:11]
	v_mfma_f32_16x16x32_bf16 v[4:7], v[148:151], v[212:215], v[4:7]
	v_mfma_f32_16x16x32_bf16 v[0:3], v[156:159], v[212:215], v[0:3]
	s_setprio 0
	s_barrier
	s_add_i32 s81, 0, 0x18000
	s_add_i32 s82, 0, 0x1c000
	v_add_u32_e32 v140, s81, v197
	v_add_u32_e32 v156, s82, v197
	ds_read_b128 v[128:131], v140
	ds_read_b128 v[132:135], v140 offset:1024
	ds_read_b128 v[136:139], v140 offset:2048
	ds_read_b128 v[140:143], v140 offset:3072
	ds_read_b128 v[144:147], v156
	ds_read_b128 v[148:151], v156 offset:1024
	ds_read_b128 v[152:155], v156 offset:2048
	ds_read_b128 v[156:159], v156 offset:3072
	s_add_u32 s36, s36, 0x80000
	s_addc_u32 s37, s37, 0
	s_mov_b32 m0, s42
	ds_read_b128 v[160:163], v199 offset:32768
	ds_read_b128 v[164:167], v199 offset:33792
	ds_read_b128 v[168:171], v199 offset:34816
	ds_read_b128 v[172:175], v199 offset:35840
	ds_read_b128 v[200:203], v199 offset:36864
	ds_read_b128 v[204:207], v199 offset:37888
	ds_read_b128 v[208:211], v199 offset:38912
	ds_read_b128 v[212:215], v199 offset:39936
	global_load_lds_dwordx4 v182, s[36:37]
	s_mov_b32 m0, s43
	s_nop 0
	global_load_lds_dwordx4 v178, s[36:37]
	s_waitcnt vmcnt(8)
	s_waitcnt lgkmcnt(0)
	s_barrier
	s_setprio 1
	s_waitcnt lgkmcnt(0)
	v_mfma_f32_16x16x32_bf16 v[124:127], v[128:131], v[160:163], v[124:127]
	v_mfma_f32_16x16x32_bf16 v[120:123], v[136:139], v[160:163], v[120:123]
	v_mfma_f32_16x16x32_bf16 v[116:119], v[128:131], v[168:171], v[116:119]
	v_mfma_f32_16x16x32_bf16 v[112:115], v[136:139], v[168:171], v[112:115]
	v_mfma_f32_16x16x32_bf16 v[108:111], v[128:131], v[200:203], v[108:111]
	v_mfma_f32_16x16x32_bf16 v[104:107], v[136:139], v[200:203], v[104:107]
	v_mfma_f32_16x16x32_bf16 v[100:103], v[128:131], v[208:211], v[100:103]
	v_mfma_f32_16x16x32_bf16 v[96:99], v[136:139], v[208:211], v[96:99]
	v_mfma_f32_16x16x32_bf16 v[124:127], v[132:135], v[164:167], v[124:127]
	v_mfma_f32_16x16x32_bf16 v[120:123], v[140:143], v[164:167], v[120:123]
	v_mfma_f32_16x16x32_bf16 v[116:119], v[132:135], v[172:175], v[116:119]
	v_mfma_f32_16x16x32_bf16 v[112:115], v[140:143], v[172:175], v[112:115]
	v_mfma_f32_16x16x32_bf16 v[108:111], v[132:135], v[204:207], v[108:111]
	v_mfma_f32_16x16x32_bf16 v[104:107], v[140:143], v[204:207], v[104:107]
	v_mfma_f32_16x16x32_bf16 v[100:103], v[132:135], v[212:215], v[100:103]
	v_mfma_f32_16x16x32_bf16 v[96:99], v[140:143], v[212:215], v[96:99]
	s_setprio 0
	s_setprio 1
	v_mfma_f32_16x16x32_bf16 v[92:95], v[144:147], v[160:163], v[92:95]
	v_mfma_f32_16x16x32_bf16 v[88:91], v[152:155], v[160:163], v[88:91]
	v_mfma_f32_16x16x32_bf16 v[84:87], v[144:147], v[168:171], v[84:87]
	v_mfma_f32_16x16x32_bf16 v[80:83], v[152:155], v[168:171], v[80:83]
	v_mfma_f32_16x16x32_bf16 v[76:79], v[144:147], v[200:203], v[76:79]
	v_mfma_f32_16x16x32_bf16 v[72:75], v[152:155], v[200:203], v[72:75]
	v_mfma_f32_16x16x32_bf16 v[68:71], v[144:147], v[208:211], v[68:71]
	v_mfma_f32_16x16x32_bf16 v[64:67], v[152:155], v[208:211], v[64:67]
	v_mfma_f32_16x16x32_bf16 v[92:95], v[148:151], v[164:167], v[92:95]
	v_mfma_f32_16x16x32_bf16 v[88:91], v[156:159], v[164:167], v[88:91]
	v_mfma_f32_16x16x32_bf16 v[84:87], v[148:151], v[172:175], v[84:87]
	v_mfma_f32_16x16x32_bf16 v[80:83], v[156:159], v[172:175], v[80:83]
	v_mfma_f32_16x16x32_bf16 v[76:79], v[148:151], v[204:207], v[76:79]
	v_mfma_f32_16x16x32_bf16 v[72:75], v[156:159], v[204:207], v[72:75]
	v_mfma_f32_16x16x32_bf16 v[68:71], v[148:151], v[212:215], v[68:71]
	v_mfma_f32_16x16x32_bf16 v[64:67], v[156:159], v[212:215], v[64:67]
	s_setprio 0
	s_barrier
; #define PG8_STAGE(bufoff, gbase, voff) do { _Pragma("unroll") for (int _i = 0; _i < 2; ++_i) \
;         __builtin_amdgcn_global_load_lds((const unsigned*)((const char*)(gbase) + (voff)[_i]), (LAS unsigned*)(lds + (bufoff) + ldsw + _i * 8192), 16, 0, 0); } while (0)
; #define PG8_LDA(dst, b, h) do { _Pragma("unroll") for (int m = 0; m < 4; ++m) _Pragma("unroll") for (int k = 0; k < 2; ++k) dst[m][k] = *(const LAS bf16x8*)(lds + PG8_SA(b, h) + aoff + m * 2048 + k * 1024); } while (0)
; #define PG8_WAIT_V(n) asm volatile("s_waitcnt vmcnt(" #n ")" ::: "memory")
; #define PG8_WAIT_L(n) asm volatile("s_waitcnt lgkmcnt(" #n ")" ::: "memory")
; #define PG8_BAR __builtin_amdgcn_s_barrier()
; #define PG8_SCHED __builtin_amdgcn_sched_barrier(0)
; template <class Epi, class Sched, bool F8 = false>
; __device__ __forceinline__ void gemm_phase(LAS unsigned char* lds, const Gemm g, const Sched& S, const Epi& E) {
;     ...
;             PG8_LDA(At, 1, 1); PG8_STAGE(PG8_SB(1, 0), b3, voffB); PG8_STAGE(PG8_SB(1, 1), b3 + hstepB, voffB); PG8_STAGE(PG8_SA(1, 0), a3, voffA);
;             PG8_WAIT_V(8); PG8_WAIT_L(0); PG8_BAR; PG8_MMA(1, 0, At, B0); PG8_MMA(1, 1, At, B1); PG8_BAR; PG8_SCHED;
;         }
	s_add_i32 s36, s81, s38
	s_add_i32 m0, s36, 0xffffff80
	ds_read_b128 v[160:163], v199 offset:49152
	ds_read_b128 v[164:167], v199 offset:50176
	ds_read_b128 v[168:171], v199 offset:51200
	ds_read_b128 v[172:175], v199 offset:52224
	ds_read_b128 v[200:203], v199 offset:53248
	ds_read_b128 v[204:207], v199 offset:54272
	ds_read_b128 v[208:211], v199 offset:55296
	ds_read_b128 v[212:215], v199 offset:56320
	global_load_lds_dwordx4 v[216:217], off offset:128
	s_add_i32 m0, s36, 0x1f80
	s_add_u32 s34, s34, 0x80080
	s_addc_u32 s35, s35, 0
	s_add_i32 s36, s82, s38
	global_load_lds_dwordx4 v[218:219], off offset:128
	s_mov_b32 m0, s36
	s_nop 0
	global_load_lds_dwordx4 v180, s[34:35]
	s_add_i32 m0, s36, 0x2000
	s_nop 0
	global_load_lds_dwordx4 v176, s[34:35]
	s_add_i32 m0, s45, 0xffffff80
	s_nop 0
	global_load_lds_dwordx4 v[220:221], off offset:128
	s_add_i32 m0, s47, 0xffffff80
	s_nop 0
	global_load_lds_dwordx4 v[222:223], off offset:128
	s_waitcnt vmcnt(8)
	s_waitcnt lgkmcnt(0)
	s_barrier
	s_setprio 1
	s_waitcnt lgkmcnt(0)
	v_mfma_f32_16x16x32_bf16 v[60:63], v[128:131], v[160:163], v[60:63]
	v_mfma_f32_16x16x32_bf16 v[56:59], v[136:139], v[160:163], v[56:59]
	v_mfma_f32_16x16x32_bf16 v[52:55], v[128:131], v[168:171], v[52:55]
	v_mfma_f32_16x16x32_bf16 v[48:51], v[136:139], v[168:171], v[48:51]
	v_mfma_f32_16x16x32_bf16 v[44:47], v[128:131], v[200:203], v[44:47]
	v_mfma_f32_16x16x32_bf16 v[40:43], v[136:139], v[200:203], v[40:43]
	v_mfma_f32_16x16x32_bf16 v[36:39], v[128:131], v[208:211], v[36:39]
	v_mfma_f32_16x16x32_bf16 v[32:35], v[136:139], v[208:211], v[32:35]
	v_mfma_f32_16x16x32_bf16 v[60:63], v[132:135], v[164:167], v[60:63]
	v_mfma_f32_16x16x32_bf16 v[56:59], v[140:143], v[164:167], v[56:59]
	v_mfma_f32_16x16x32_bf16 v[52:55], v[132:135], v[172:175], v[52:55]
	v_mfma_f32_16x16x32_bf16 v[48:51], v[140:143], v[172:175], v[48:51]
	v_mfma_f32_16x16x32_bf16 v[44:47], v[132:135], v[204:207], v[44:47]
	v_mfma_f32_16x16x32_bf16 v[40:43], v[140:143], v[204:207], v[40:43]
	v_mfma_f32_16x16x32_bf16 v[36:39], v[132:135], v[212:215], v[36:39]
	v_mfma_f32_16x16x32_bf16 v[32:35], v[140:143], v[212:215], v[32:35]
	s_setprio 0
	s_setprio 1
	v_mfma_f32_16x16x32_bf16 v[28:31], v[144:147], v[160:163], v[28:31]
	v_mfma_f32_16x16x32_bf16 v[24:27], v[152:155], v[160:163], v[24:27]
	v_mfma_f32_16x16x32_bf16 v[20:23], v[144:147], v[168:171], v[20:23]
	v_mfma_f32_16x16x32_bf16 v[16:19], v[152:155], v[168:171], v[16:19]
	v_mfma_f32_16x16x32_bf16 v[12:15], v[144:147], v[200:203], v[12:15]
	v_mfma_f32_16x16x32_bf16 v[8:11], v[152:155], v[200:203], v[8:11]
	v_mfma_f32_16x16x32_bf16 v[4:7], v[144:147], v[208:211], v[4:7]
	v_mfma_f32_16x16x32_bf16 v[0:3], v[152:155], v[208:211], v[0:3]
	v_mfma_f32_16x16x32_bf16 v[28:31], v[148:151], v[164:167], v[28:31]
	v_mfma_f32_16x16x32_bf16 v[24:27], v[156:159], v[164:167], v[24:27]
	v_mfma_f32_16x16x32_bf16 v[20:23], v[148:151], v[172:175], v[20:23]
	v_mfma_f32_16x16x32_bf16 v[16:19], v[156:159], v[172:175], v[16:19]
	v_mfma_f32_16x16x32_bf16 v[12:15], v[148:151], v[204:207], v[12:15]
	v_mfma_f32_16x16x32_bf16 v[8:11], v[156:159], v[204:207], v[8:11]
	v_mfma_f32_16x16x32_bf16 v[4:7], v[148:151], v[212:215], v[4:7]
	v_mfma_f32_16x16x32_bf16 v[0:3], v[156:159], v[212:215], v[0:3]
	s_setprio 0
	s_add_u32 s30, s30, 0x100
	s_addc_u32 s31, s31, 0
	s_add_u32 s78, s78, 0x100
	s_addc_u32 s79, s79, 0
	s_cmp_ge_i32 s80, s9
	s_mov_b32 s34, s80
	s_barrier
	s_cbranch_scc0 .LBB0_753
	s_and_b64 vcc, exec, s[18:19]
	s_cbranch_vccz .LBB0_756
	s_barrier

; #define PG8_STAGE(bufoff, gbase, voff) do { _Pragma("unroll") for (int _i = 0; _i < 2; ++_i) \
;         __builtin_amdgcn_global_load_lds((const unsigned*)((const char*)(gbase) + (voff)[_i]), (LAS unsigned*)(lds + (bufoff) + ldsw + _i * 8192), 16, 0, 0); } while (0)
; #define PG8_LDA(dst, b, h) do { _Pragma("unroll") for (int m = 0; m < 4; ++m) _Pragma("unroll") for (int k = 0; k < 2; ++k) dst[m][k] = *(const LAS bf16x8*)(lds + PG8_SA(b, h) + aoff + m * 2048 + k * 1024); } while (0)
; #define PG8_LDB(dst, b, h) do { _Pragma("unroll") for (int n = 0; n < 2; ++n) _Pragma("unroll") for (int k = 0; k < 2; ++k) dst[n][k] = *(const LAS bf16x8*)(lds + PG8_SB(b, h) + boff + n * 2048 + k * 1024); } while (0)
; #define PG8_WAIT_V(n) asm volatile("s_waitcnt vmcnt(" #n ")" ::: "memory")
; #define PG8_WAIT_L(n) asm volatile("s_waitcnt lgkmcnt(" #n ")" ::: "memory")
; #define PG8_BAR __builtin_amdgcn_s_barrier()
; #define PG8_SCHED __builtin_amdgcn_sched_barrier(0)
; template <class Epi, class Sched, bool F8 = false>
; __device__ __forceinline__ void gemm_phase(LAS unsigned char* lds, const Gemm g, const Sched& S, const Epi& E) {
;     ...
;         for (int t = 0; t < nt; t += 2) {
;             const bool last = (t == nt - 2);
;             const char* a1 = cA + (size_t)(t + 1) * kstep;
;             const char* a2 = last ? nA : cA + (size_t)(t + 2) * kstep; const char* b2 = last ? nB : cB + (size_t)(t + 2) * kstep;
;             const char* a3 = a2 + kstep; const char* b3 = b2 + kstep;
;             PG8_LDB(B0, 0, 0); PG8_LDB(B1, 0, 1); PG8_SCHED; PG8_LDA(At, 0, 0); PG8_STAGE(PG8_SA(1, 1), a1 + hstepA, voffA);
;             PG8_WAIT_V(8); PG8_WAIT_L(0); PG8_BAR; PG8_MMA(0, 0, At, B0); PG8_MMA(0, 1, At, B1); PG8_BAR; PG8_SCHED;
;             PG8_LDA(At, 0, 1); PG8_STAGE(PG8_SB(0, 0), b2, voffB); PG8_STAGE(PG8_SB(0, 1), b2 + hstepB, voffB); PG8_STAGE(PG8_SA(0, 0), a2, voffA);
;             PG8_WAIT_V(8); PG8_WAIT_L(0); PG8_BAR; PG8_MMA(1, 0, At, B0); PG8_MMA(1, 1, At, B1); PG8_BAR; PG8_SCHED;
.LBB0_825:
	ds_read_b128 v[168:171], v164
	ds_read_b128 v[172:175], v164 offset:1024
	ds_read_b128 v[176:179], v164 offset:2048
	ds_read_b128 v[180:183], v164 offset:3072
	ds_read_b128 v[184:187], v165
	ds_read_b128 v[192:195], v165 offset:1024
	ds_read_b128 v[196:199], v165 offset:2048
	ds_read_b128 v[200:203], v165 offset:3072
	s_add_u32 s38, s36, 0xfff80080
	s_addc_u32 s39, s37, -1
	s_cmp_eq_u32 s58, 28
	s_cselect_b32 s41, s10, s39
	s_cselect_b32 s40, s27, s38
	s_cselect_b32 s39, s25, s57
	s_cselect_b32 s38, s35, s56
	s_add_i32 m0, s43, 0xc000
	ds_read_b128 v[204:207], v166
	ds_read_b128 v[208:211], v166 offset:1024
	ds_read_b128 v[212:215], v166 offset:2048
	ds_read_b128 v[216:219], v166 offset:3072
	ds_read_b128 v[220:223], v166 offset:4096
	ds_read_b128 v[224:227], v166 offset:5120
	ds_read_b128 v[228:231], v166 offset:6144
	ds_read_b128 v[232:235], v166 offset:7168
	global_load_lds_dwordx4 v152, s[36:37]
	s_add_i32 m0, s43, 0xe000
	s_nop 0
	global_load_lds_dwordx4 v154, s[36:37]
	s_waitcnt vmcnt(8)
	s_waitcnt lgkmcnt(0)
	s_barrier
	s_setprio 1
	s_waitcnt lgkmcnt(0)
	v_mfma_f32_16x16x32_bf16 v[124:127], v[168:171], v[204:207], v[124:127]
	v_mfma_f32_16x16x32_bf16 v[120:123], v[176:179], v[204:207], v[120:123]
	v_mfma_f32_16x16x32_bf16 v[116:119], v[168:171], v[212:215], v[116:119]
	v_mfma_f32_16x16x32_bf16 v[108:111], v[176:179], v[212:215], v[108:111]
	v_mfma_f32_16x16x32_bf16 v[100:103], v[168:171], v[220:223], v[100:103]
	v_mfma_f32_16x16x32_bf16 v[92:95], v[176:179], v[220:223], v[92:95]
	v_mfma_f32_16x16x32_bf16 v[84:87], v[168:171], v[228:231], v[84:87]
	v_mfma_f32_16x16x32_bf16 v[76:79], v[176:179], v[228:231], v[76:79]
	v_mfma_f32_16x16x32_bf16 v[124:127], v[172:175], v[208:211], v[124:127]
	v_mfma_f32_16x16x32_bf16 v[120:123], v[180:183], v[208:211], v[120:123]
	v_mfma_f32_16x16x32_bf16 v[116:119], v[172:175], v[216:219], v[116:119]
	v_mfma_f32_16x16x32_bf16 v[108:111], v[180:183], v[216:219], v[108:111]
	v_mfma_f32_16x16x32_bf16 v[100:103], v[172:175], v[224:227], v[100:103]
	v_mfma_f32_16x16x32_bf16 v[92:95], v[180:183], v[224:227], v[92:95]
	v_mfma_f32_16x16x32_bf16 v[84:87], v[172:175], v[232:235], v[84:87]
	v_mfma_f32_16x16x32_bf16 v[76:79], v[180:183], v[232:235], v[76:79]
	s_setprio 0
	s_setprio 1
	v_mfma_f32_16x16x32_bf16 v[112:115], v[184:187], v[204:207], v[112:115]
	v_mfma_f32_16x16x32_bf16 v[104:107], v[196:199], v[204:207], v[104:107]
	v_mfma_f32_16x16x32_bf16 v[96:99], v[184:187], v[212:215], v[96:99]
	v_mfma_f32_16x16x32_bf16 v[88:91], v[196:199], v[212:215], v[88:91]
	v_mfma_f32_16x16x32_bf16 v[80:83], v[184:187], v[220:223], v[80:83]
	v_mfma_f32_16x16x32_bf16 v[72:75], v[196:199], v[220:223], v[72:75]
	v_mfma_f32_16x16x32_bf16 v[68:71], v[184:187], v[228:231], v[68:71]
	v_mfma_f32_16x16x32_bf16 v[64:67], v[196:199], v[228:231], v[64:67]
	v_mfma_f32_16x16x32_bf16 v[112:115], v[192:195], v[208:211], v[112:115]
	v_mfma_f32_16x16x32_bf16 v[104:107], v[200:203], v[208:211], v[104:107]
	v_mfma_f32_16x16x32_bf16 v[96:99], v[192:195], v[216:219], v[96:99]
	v_mfma_f32_16x16x32_bf16 v[88:91], v[200:203], v[216:219], v[88:91]
	v_mfma_f32_16x16x32_bf16 v[80:83], v[192:195], v[224:227], v[80:83]
	v_mfma_f32_16x16x32_bf16 v[72:75], v[200:203], v[224:227], v[72:75]
	v_mfma_f32_16x16x32_bf16 v[68:71], v[192:195], v[232:235], v[68:71]
	v_mfma_f32_16x16x32_bf16 v[64:67], v[200:203], v[232:235], v[64:67]
	s_setprio 0
	s_barrier
	s_add_i32 s59, s50, s23
	v_lshl_add_u64 v[160:161], s[38:39], 0, v[132:133]
	s_mov_b32 m0, s59
	ds_read_b128 v[204:207], v166 offset:16384
	ds_read_b128 v[208:211], v166 offset:17408
	ds_read_b128 v[212:215], v166 offset:18432
	ds_read_b128 v[216:219], v166 offset:19456
	ds_read_b128 v[220:223], v166 offset:20480
	ds_read_b128 v[224:227], v166 offset:21504
	ds_read_b128 v[228:231], v166 offset:22528
	ds_read_b128 v[232:235], v166 offset:23552
	global_load_lds_dwordx4 v[160:161], off
	s_add_i32 m0, s59, 0x2000
	s_add_u32 s72, s38, 0x80000
	v_lshl_add_u64 v[188:189], s[38:39], 0, v[128:129]
	s_addc_u32 s73, s39, 0
	s_add_i32 s59, s91, s23
	global_load_lds_dwordx4 v[188:189], off
	s_mov_b32 m0, s59
	v_lshl_add_u64 v[238:239], s[40:41], 0, v[130:131]
	global_load_lds_dwordx4 v132, s[72:73]
	s_add_i32 m0, s59, 0x2000
	s_nop 0
	global_load_lds_dwordx4 v128, s[72:73]
	v_lshl_add_u64 v[236:237], s[40:41], 0, v[134:135]
	s_mov_b32 m0, s43
	s_nop 0
	global_load_lds_dwordx4 v[236:237], off
	s_mov_b32 m0, s44
	s_nop 0
	global_load_lds_dwordx4 v[238:239], off
	s_waitcnt vmcnt(8)
	s_waitcnt lgkmcnt(0)
	s_barrier
; #define PG8_STAGE(bufoff, gbase, voff) do { _Pragma("unroll") for (int _i = 0; _i < 2; ++_i) \
;         __builtin_amdgcn_global_load_lds((const unsigned*)((const char*)(gbase) + (voff)[_i]), (LAS unsigned*)(lds + (bufoff) + ldsw + _i * 8192), 16, 0, 0); } while (0)
; #define PG8_LDA(dst, b, h) do { _Pragma("unroll") for (int m = 0; m < 4; ++m) _Pragma("unroll") for (int k = 0; k < 2; ++k) dst[m][k] = *(const LAS bf16x8*)(lds + PG8_SA(b, h) + aoff + m * 2048 + k * 1024); } while (0)
; #define PG8_LDB(dst, b, h) do { _Pragma("unroll") for (int n = 0; n < 2; ++n) _Pragma("unroll") for (int k = 0; k < 2; ++k) dst[n][k] = *(const LAS bf16x8*)(lds + PG8_SB(b, h) + boff + n * 2048 + k * 1024); } while (0)
; #define PG8_WAIT_V(n) asm volatile("s_waitcnt vmcnt(" #n ")" ::: "memory")
; #define PG8_WAIT_L(n) asm volatile("s_waitcnt lgkmcnt(" #n ")" ::: "memory")
; #define PG8_BAR __builtin_amdgcn_s_barrier()
; #define PG8_SCHED __builtin_amdgcn_sched_barrier(0)
; template <class Epi, class Sched, bool F8 = false>
; __device__ __forceinline__ void gemm_phase(LAS unsigned char* lds, const Gemm g, const Sched& S, const Epi& E) {
;     ...
;             PG8_WAIT_V(8); PG8_WAIT_L(0); PG8_BAR; PG8_MMA(1, 0, At, B0); PG8_MMA(1, 1, At, B1); PG8_BAR; PG8_SCHED;
;             PG8_LDB(B0, 1, 0); PG8_LDB(B1, 1, 1); PG8_SCHED; PG8_LDA(At, 1, 0); PG8_STAGE(PG8_SA(0, 1), a2 + hstepA, voffA);
;             PG8_WAIT_V(8); PG8_WAIT_L(0); PG8_BAR; PG8_MMA(0, 0, At, B0); PG8_MMA(0, 1, At, B1); PG8_BAR; PG8_SCHED;
	s_setprio 1
	s_waitcnt lgkmcnt(0)
	v_mfma_f32_16x16x32_bf16 v[60:63], v[168:171], v[204:207], v[60:63]
	v_mfma_f32_16x16x32_bf16 v[56:59], v[176:179], v[204:207], v[56:59]
	v_mfma_f32_16x16x32_bf16 v[52:55], v[168:171], v[212:215], v[52:55]
	v_mfma_f32_16x16x32_bf16 v[44:47], v[176:179], v[212:215], v[44:47]
	v_mfma_f32_16x16x32_bf16 v[36:39], v[168:171], v[220:223], v[36:39]
	v_mfma_f32_16x16x32_bf16 v[28:31], v[176:179], v[220:223], v[28:31]
	v_mfma_f32_16x16x32_bf16 v[20:23], v[168:171], v[228:231], v[20:23]
	v_mfma_f32_16x16x32_bf16 v[12:15], v[176:179], v[228:231], v[12:15]
	v_mfma_f32_16x16x32_bf16 v[60:63], v[172:175], v[208:211], v[60:63]
	v_mfma_f32_16x16x32_bf16 v[56:59], v[180:183], v[208:211], v[56:59]
	v_mfma_f32_16x16x32_bf16 v[52:55], v[172:175], v[216:219], v[52:55]
	v_mfma_f32_16x16x32_bf16 v[44:47], v[180:183], v[216:219], v[44:47]
	v_mfma_f32_16x16x32_bf16 v[36:39], v[172:175], v[224:227], v[36:39]
	v_mfma_f32_16x16x32_bf16 v[28:31], v[180:183], v[224:227], v[28:31]
	v_mfma_f32_16x16x32_bf16 v[20:23], v[172:175], v[232:235], v[20:23]
	v_mfma_f32_16x16x32_bf16 v[12:15], v[180:183], v[232:235], v[12:15]
	s_setprio 0
	s_setprio 1
	v_mfma_f32_16x16x32_bf16 v[48:51], v[184:187], v[204:207], v[48:51]
	v_mfma_f32_16x16x32_bf16 v[40:43], v[196:199], v[204:207], v[40:43]
	v_mfma_f32_16x16x32_bf16 v[32:35], v[184:187], v[212:215], v[32:35]
	v_mfma_f32_16x16x32_bf16 v[24:27], v[196:199], v[212:215], v[24:27]
	v_mfma_f32_16x16x32_bf16 v[16:19], v[184:187], v[220:223], v[16:19]
	v_mfma_f32_16x16x32_bf16 v[8:11], v[196:199], v[220:223], v[8:11]
	v_mfma_f32_16x16x32_bf16 v[4:7], v[184:187], v[228:231], v[4:7]
	v_mfma_f32_16x16x32_bf16 v[0:3], v[196:199], v[228:231], v[0:3]
	v_mfma_f32_16x16x32_bf16 v[48:51], v[192:195], v[208:211], v[48:51]
	v_mfma_f32_16x16x32_bf16 v[40:43], v[200:203], v[208:211], v[40:43]
	v_mfma_f32_16x16x32_bf16 v[32:35], v[192:195], v[216:219], v[32:35]
	v_mfma_f32_16x16x32_bf16 v[24:27], v[200:203], v[216:219], v[24:27]
	v_mfma_f32_16x16x32_bf16 v[16:19], v[192:195], v[224:227], v[16:19]
	v_mfma_f32_16x16x32_bf16 v[8:11], v[200:203], v[224:227], v[8:11]
	v_mfma_f32_16x16x32_bf16 v[4:7], v[192:195], v[232:235], v[4:7]
	v_mfma_f32_16x16x32_bf16 v[0:3], v[200:203], v[232:235], v[0:3]
	s_setprio 0
	s_barrier
	s_add_i32 s59, 0, 0x18000
	v_add_u32_e32 v167, s59, v162
	s_add_i32 s72, 0, 0x1c000
	ds_read_b128 v[168:171], v167
	ds_read_b128 v[172:175], v167 offset:1024
	ds_read_b128 v[176:179], v167 offset:2048
	ds_read_b128 v[180:183], v167 offset:3072
	v_add_u32_e32 v167, s72, v162
	ds_read_b128 v[184:187], v167
	ds_read_b128 v[192:195], v167 offset:1024
	ds_read_b128 v[196:199], v167 offset:2048
	ds_read_b128 v[200:203], v167 offset:3072
	s_add_u32 s40, s40, 0x80000
	s_addc_u32 s41, s41, 0
	s_mov_b32 m0, s45
	ds_read_b128 v[204:207], v166 offset:32768
	ds_read_b128 v[208:211], v166 offset:33792
	ds_read_b128 v[212:215], v166 offset:34816
	ds_read_b128 v[216:219], v166 offset:35840
	ds_read_b128 v[220:223], v166 offset:36864
	ds_read_b128 v[224:227], v166 offset:37888
	ds_read_b128 v[228:231], v166 offset:38912
	ds_read_b128 v[232:235], v166 offset:39936
	global_load_lds_dwordx4 v134, s[40:41]
	s_mov_b32 m0, s47
	s_nop 0
	global_load_lds_dwordx4 v130, s[40:41]
	s_waitcnt vmcnt(8)
	s_waitcnt lgkmcnt(0)
	s_barrier
	s_setprio 1
	s_waitcnt lgkmcnt(0)
	v_mfma_f32_16x16x32_bf16 v[124:127], v[168:171], v[204:207], v[124:127]
	v_mfma_f32_16x16x32_bf16 v[120:123], v[176:179], v[204:207], v[120:123]
	v_mfma_f32_16x16x32_bf16 v[116:119], v[168:171], v[212:215], v[116:119]
	v_mfma_f32_16x16x32_bf16 v[108:111], v[176:179], v[212:215], v[108:111]
	v_mfma_f32_16x16x32_bf16 v[100:103], v[168:171], v[220:223], v[100:103]
	v_mfma_f32_16x16x32_bf16 v[92:95], v[176:179], v[220:223], v[92:95]
	v_mfma_f32_16x16x32_bf16 v[84:87], v[168:171], v[228:231], v[84:87]
	v_mfma_f32_16x16x32_bf16 v[76:79], v[176:179], v[228:231], v[76:79]
	v_mfma_f32_16x16x32_bf16 v[124:127], v[172:175], v[208:211], v[124:127]
	v_mfma_f32_16x16x32_bf16 v[120:123], v[180:183], v[208:211], v[120:123]
	v_mfma_f32_16x16x32_bf16 v[116:119], v[172:175], v[216:219], v[116:119]
	v_mfma_f32_16x16x32_bf16 v[108:111], v[180:183], v[216:219], v[108:111]
	v_mfma_f32_16x16x32_bf16 v[100:103], v[172:175], v[224:227], v[100:103]
	v_mfma_f32_16x16x32_bf16 v[92:95], v[180:183], v[224:227], v[92:95]
	v_mfma_f32_16x16x32_bf16 v[84:87], v[172:175], v[232:235], v[84:87]
	v_mfma_f32_16x16x32_bf16 v[76:79], v[180:183], v[232:235], v[76:79]
	s_setprio 0
	s_setprio 1
	v_mfma_f32_16x16x32_bf16 v[112:115], v[184:187], v[204:207], v[112:115]
	v_mfma_f32_16x16x32_bf16 v[104:107], v[196:199], v[204:207], v[104:107]
	v_mfma_f32_16x16x32_bf16 v[96:99], v[184:187], v[212:215], v[96:99]
	v_mfma_f32_16x16x32_bf16 v[88:91], v[196:199], v[212:215], v[88:91]
	v_mfma_f32_16x16x32_bf16 v[80:83], v[184:187], v[220:223], v[80:83]
	v_mfma_f32_16x16x32_bf16 v[72:75], v[196:199], v[220:223], v[72:75]
	v_mfma_f32_16x16x32_bf16 v[68:71], v[184:187], v[228:231], v[68:71]
	v_mfma_f32_16x16x32_bf16 v[64:67], v[196:199], v[228:231], v[64:67]
	v_mfma_f32_16x16x32_bf16 v[112:115], v[192:195], v[208:211], v[112:115]
	v_mfma_f32_16x16x32_bf16 v[104:107], v[200:203], v[208:211], v[104:107]
	v_mfma_f32_16x16x32_bf16 v[96:99], v[192:195], v[216:219], v[96:99]
	v_mfma_f32_16x16x32_bf16 v[88:91], v[200:203], v[216:219], v[88:91]
	v_mfma_f32_16x16x32_bf16 v[80:83], v[192:195], v[224:227], v[80:83]
	v_mfma_f32_16x16x32_bf16 v[72:75], v[200:203], v[224:227], v[72:75]
	v_mfma_f32_16x16x32_bf16 v[68:71], v[192:195], v[232:235], v[68:71]
	v_mfma_f32_16x16x32_bf16 v[64:67], v[200:203], v[232:235], v[64:67]
	s_setprio 0
	s_barrier
; #define PG8_STAGE(bufoff, gbase, voff) do { _Pragma("unroll") for (int _i = 0; _i < 2; ++_i) \
;         __builtin_amdgcn_global_load_lds((const unsigned*)((const char*)(gbase) + (voff)[_i]), (LAS unsigned*)(lds + (bufoff) + ldsw + _i * 8192), 16, 0, 0); } while (0)
; #define PG8_LDA(dst, b, h) do { _Pragma("unroll") for (int m = 0; m < 4; ++m) _Pragma("unroll") for (int k = 0; k < 2; ++k) dst[m][k] = *(const LAS bf16x8*)(lds + PG8_SA(b, h) + aoff + m * 2048 + k * 1024); } while (0)
; #define PG8_WAIT_V(n) asm volatile("s_waitcnt vmcnt(" #n ")" ::: "memory")
; #define PG8_WAIT_L(n) asm volatile("s_waitcnt lgkmcnt(" #n ")" ::: "memory")
; #define PG8_BAR __builtin_amdgcn_s_barrier()
; #define PG8_SCHED __builtin_amdgcn_sched_barrier(0)
; template <class Epi, class Sched, bool F8 = false>
; __device__ __forceinline__ void gemm_phase(LAS unsigned char* lds, const Gemm g, const Sched& S, const Epi& E) {
;     ...
;             PG8_LDA(At, 1, 1); PG8_STAGE(PG8_SB(1, 0), b3, voffB); PG8_STAGE(PG8_SB(1, 1), b3 + hstepB, voffB); PG8_STAGE(PG8_SA(1, 0), a3, voffA);
;             PG8_WAIT_V(8); PG8_WAIT_L(0); PG8_BAR; PG8_MMA(1, 0, At, B0); PG8_MMA(1, 1, At, B1); PG8_BAR; PG8_SCHED;
;         }
	s_add_i32 s40, s59, s23
	s_add_i32 m0, s40, 0xffffff80
	ds_read_b128 v[204:207], v166 offset:49152
	ds_read_b128 v[208:211], v166 offset:50176
	ds_read_b128 v[212:215], v166 offset:51200
	ds_read_b128 v[216:219], v166 offset:52224
	ds_read_b128 v[220:223], v166 offset:53248
	ds_read_b128 v[224:227], v166 offset:54272
	ds_read_b128 v[228:231], v166 offset:55296
	ds_read_b128 v[232:235], v166 offset:56320
	global_load_lds_dwordx4 v[160:161], off offset:128
	s_add_i32 m0, s40, 0x1f80
	s_add_u32 s38, s38, 0x80080
	s_addc_u32 s39, s39, 0
	s_add_i32 s40, s72, s23
	global_load_lds_dwordx4 v[188:189], off offset:128
	s_mov_b32 m0, s40
	s_nop 0
	global_load_lds_dwordx4 v132, s[38:39]
	s_add_i32 m0, s40, 0x2000
	s_nop 0
	global_load_lds_dwordx4 v128, s[38:39]
	s_add_i32 m0, s48, 0xffffff80
	s_nop 0
	global_load_lds_dwordx4 v[236:237], off offset:128
	s_add_i32 m0, s49, 0xffffff80
	s_nop 0
	global_load_lds_dwordx4 v[238:239], off offset:128
	s_waitcnt vmcnt(8)
	s_waitcnt lgkmcnt(0)
	s_barrier
	s_setprio 1
	s_waitcnt lgkmcnt(0)
	v_mfma_f32_16x16x32_bf16 v[60:63], v[168:171], v[204:207], v[60:63]
	v_mfma_f32_16x16x32_bf16 v[56:59], v[176:179], v[204:207], v[56:59]
	v_mfma_f32_16x16x32_bf16 v[52:55], v[168:171], v[212:215], v[52:55]
	v_mfma_f32_16x16x32_bf16 v[44:47], v[176:179], v[212:215], v[44:47]
	v_mfma_f32_16x16x32_bf16 v[36:39], v[168:171], v[220:223], v[36:39]
	v_mfma_f32_16x16x32_bf16 v[28:31], v[176:179], v[220:223], v[28:31]
	v_mfma_f32_16x16x32_bf16 v[20:23], v[168:171], v[228:231], v[20:23]
	v_mfma_f32_16x16x32_bf16 v[12:15], v[176:179], v[228:231], v[12:15]
	v_mfma_f32_16x16x32_bf16 v[60:63], v[172:175], v[208:211], v[60:63]
	v_mfma_f32_16x16x32_bf16 v[56:59], v[180:183], v[208:211], v[56:59]
	v_mfma_f32_16x16x32_bf16 v[52:55], v[172:175], v[216:219], v[52:55]
	v_mfma_f32_16x16x32_bf16 v[44:47], v[180:183], v[216:219], v[44:47]
	v_mfma_f32_16x16x32_bf16 v[36:39], v[172:175], v[224:227], v[36:39]
	v_mfma_f32_16x16x32_bf16 v[28:31], v[180:183], v[224:227], v[28:31]
	v_mfma_f32_16x16x32_bf16 v[20:23], v[172:175], v[232:235], v[20:23]
	v_mfma_f32_16x16x32_bf16 v[12:15], v[180:183], v[232:235], v[12:15]
	s_setprio 0
	s_setprio 1
	v_mfma_f32_16x16x32_bf16 v[48:51], v[184:187], v[204:207], v[48:51]
	v_mfma_f32_16x16x32_bf16 v[40:43], v[196:199], v[204:207], v[40:43]
	v_mfma_f32_16x16x32_bf16 v[32:35], v[184:187], v[212:215], v[32:35]
	v_mfma_f32_16x16x32_bf16 v[24:27], v[196:199], v[212:215], v[24:27]
	v_mfma_f32_16x16x32_bf16 v[16:19], v[184:187], v[220:223], v[16:19]
	v_mfma_f32_16x16x32_bf16 v[8:11], v[196:199], v[220:223], v[8:11]
	v_mfma_f32_16x16x32_bf16 v[4:7], v[184:187], v[228:231], v[4:7]
	v_mfma_f32_16x16x32_bf16 v[0:3], v[196:199], v[228:231], v[0:3]
	v_mfma_f32_16x16x32_bf16 v[48:51], v[192:195], v[208:211], v[48:51]
	v_mfma_f32_16x16x32_bf16 v[40:43], v[200:203], v[208:211], v[40:43]
	v_mfma_f32_16x16x32_bf16 v[32:35], v[192:195], v[216:219], v[32:35]
	v_mfma_f32_16x16x32_bf16 v[24:27], v[200:203], v[216:219], v[24:27]
	v_mfma_f32_16x16x32_bf16 v[16:19], v[192:195], v[224:227], v[16:19]
	v_mfma_f32_16x16x32_bf16 v[8:11], v[200:203], v[224:227], v[8:11]
	v_mfma_f32_16x16x32_bf16 v[4:7], v[192:195], v[232:235], v[4:7]
	v_mfma_f32_16x16x32_bf16 v[0:3], v[200:203], v[232:235], v[0:3]
	s_setprio 0
	s_add_i32 s58, s58, 2
	s_add_u32 s36, s36, 0x100
	s_addc_u32 s37, s37, 0
	s_add_u32 s56, s56, 0x100
	s_addc_u32 s57, s57, 0
	s_cmp_gt_u32 s58, 29
	s_barrier
	s_cbranch_scc0 .LBB0_825
	s_and_b64 vcc, exec, s[20:21]
	s_cbranch_vccz .LBB0_828
	s_barrier

; #define PG8_STAGE(bufoff, gbase, voff) do { _Pragma("unroll") for (int _i = 0; _i < 2; ++_i) \
;         __builtin_amdgcn_global_load_lds((const unsigned*)((const char*)(gbase) + (voff)[_i]), (LAS unsigned*)(lds + (bufoff) + ldsw + _i * 8192), 16, 0, 0); } while (0)
; #define PG8_LDA(dst, b, h) do { _Pragma("unroll") for (int m = 0; m < 4; ++m) _Pragma("unroll") for (int k = 0; k < 2; ++k) dst[m][k] = *(const LAS bf16x8*)(lds + PG8_SA(b, h) + aoff + m * 2048 + k * 1024); } while (0)
; #define PG8_LDB(dst, b, h) do { _Pragma("unroll") for (int n = 0; n < 2; ++n) _Pragma("unroll") for (int k = 0; k < 2; ++k) dst[n][k] = *(const LAS bf16x8*)(lds + PG8_SB(b, h) + boff + n * 2048 + k * 1024); } while (0)
; #define PG8_WAIT_V(n) asm volatile("s_waitcnt vmcnt(" #n ")" ::: "memory")
; #define PG8_WAIT_L(n) asm volatile("s_waitcnt lgkmcnt(" #n ")" ::: "memory")
; #define PG8_BAR __builtin_amdgcn_s_barrier()
; #define PG8_SCHED __builtin_amdgcn_sched_barrier(0)
; template <class Epi, class Sched, bool F8 = false>
; __device__ __forceinline__ void gemm_phase(LAS unsigned char* lds, const Gemm g, const Sched& S, const Epi& E) {
;     ...
;         for (int t = 0; t < nt; t += 2) {
;             const bool last = (t == nt - 2);
;             const char* a1 = cA + (size_t)(t + 1) * kstep;
;             const char* a2 = last ? nA : cA + (size_t)(t + 2) * kstep; const char* b2 = last ? nB : cB + (size_t)(t + 2) * kstep;
;             const char* a3 = a2 + kstep; const char* b3 = b2 + kstep;
;             PG8_LDB(B0, 0, 0); PG8_LDB(B1, 0, 1); PG8_SCHED; PG8_LDA(At, 0, 0); PG8_STAGE(PG8_SA(1, 1), a1 + hstepA, voffA);
;             PG8_WAIT_V(8); PG8_WAIT_L(0); PG8_BAR; PG8_MMA(0, 0, At, B0); PG8_MMA(0, 1, At, B1); PG8_BAR; PG8_SCHED;
;             PG8_LDA(At, 0, 1); PG8_STAGE(PG8_SB(0, 0), b2, voffB); PG8_STAGE(PG8_SB(0, 1), b2 + hstepB, voffB); PG8_STAGE(PG8_SA(0, 0), a2, voffA);
;             PG8_WAIT_V(8); PG8_WAIT_L(0); PG8_BAR; PG8_MMA(1, 0, At, B0); PG8_MMA(1, 1, At, B1); PG8_BAR; PG8_SCHED;
.LBB0_954:
	ds_read_b128 v[150:153], v147
	ds_read_b128 v[154:157], v147 offset:1024
	ds_read_b128 v[158:161], v147 offset:2048
	ds_read_b128 v[162:165], v147 offset:3072
	ds_read_b128 v[166:169], v148
	ds_read_b128 v[170:173], v148 offset:1024
	ds_read_b128 v[174:177], v148 offset:2048
	ds_read_b128 v[178:181], v148 offset:3072
	s_add_u32 s30, s28, 0xfff80080
	s_addc_u32 s31, s29, -1
	s_cmp_eq_u32 s53, 28
	s_cselect_b32 s35, s21, s31
	s_cselect_b32 s34, s48, s30
	s_cselect_b32 s31, s19, s51
	s_cselect_b32 s30, s49, s50
	s_add_i32 m0, s27, 0xc000
	ds_read_b128 v[182:185], v149
	ds_read_b128 v[186:189], v149 offset:1024
	ds_read_b128 v[192:195], v149 offset:2048
	ds_read_b128 v[196:199], v149 offset:3072
	ds_read_b128 v[200:203], v149 offset:4096
	ds_read_b128 v[204:207], v149 offset:5120
	ds_read_b128 v[208:211], v149 offset:6144
	ds_read_b128 v[212:215], v149 offset:7168
	global_load_lds_dwordx4 v136, s[28:29]
	s_add_i32 m0, s27, 0xe000
	s_nop 0
	global_load_lds_dwordx4 v138, s[28:29]
	s_waitcnt vmcnt(8)
	s_waitcnt lgkmcnt(0)
	s_barrier
	s_setprio 1
	s_waitcnt lgkmcnt(0)
	v_mfma_f32_16x16x32_bf16 v[124:127], v[150:153], v[182:185], v[124:127]
	v_mfma_f32_16x16x32_bf16 v[120:123], v[158:161], v[182:185], v[120:123]
	v_mfma_f32_16x16x32_bf16 v[108:111], v[150:153], v[192:195], v[108:111]
	v_mfma_f32_16x16x32_bf16 v[104:107], v[158:161], v[192:195], v[104:107]
	v_mfma_f32_16x16x32_bf16 v[92:95], v[150:153], v[200:203], v[92:95]
	v_mfma_f32_16x16x32_bf16 v[88:91], v[158:161], v[200:203], v[88:91]
	v_mfma_f32_16x16x32_bf16 v[76:79], v[150:153], v[208:211], v[76:79]
	v_mfma_f32_16x16x32_bf16 v[72:75], v[158:161], v[208:211], v[72:75]
	v_mfma_f32_16x16x32_bf16 v[124:127], v[154:157], v[186:189], v[124:127]
	v_mfma_f32_16x16x32_bf16 v[120:123], v[162:165], v[186:189], v[120:123]
	v_mfma_f32_16x16x32_bf16 v[108:111], v[154:157], v[196:199], v[108:111]
	v_mfma_f32_16x16x32_bf16 v[104:107], v[162:165], v[196:199], v[104:107]
	v_mfma_f32_16x16x32_bf16 v[92:95], v[154:157], v[204:207], v[92:95]
	v_mfma_f32_16x16x32_bf16 v[88:91], v[162:165], v[204:207], v[88:91]
	v_mfma_f32_16x16x32_bf16 v[76:79], v[154:157], v[212:215], v[76:79]
	v_mfma_f32_16x16x32_bf16 v[72:75], v[162:165], v[212:215], v[72:75]
	s_setprio 0
	s_setprio 1
	v_mfma_f32_16x16x32_bf16 v[116:119], v[166:169], v[182:185], v[116:119]
	v_mfma_f32_16x16x32_bf16 v[112:115], v[174:177], v[182:185], v[112:115]
	v_mfma_f32_16x16x32_bf16 v[100:103], v[166:169], v[192:195], v[100:103]
	v_mfma_f32_16x16x32_bf16 v[96:99], v[174:177], v[192:195], v[96:99]
	v_mfma_f32_16x16x32_bf16 v[84:87], v[166:169], v[200:203], v[84:87]
	v_mfma_f32_16x16x32_bf16 v[80:83], v[174:177], v[200:203], v[80:83]
	v_mfma_f32_16x16x32_bf16 v[68:71], v[166:169], v[208:211], v[68:71]
	v_mfma_f32_16x16x32_bf16 v[64:67], v[174:177], v[208:211], v[64:67]
	v_mfma_f32_16x16x32_bf16 v[116:119], v[170:173], v[186:189], v[116:119]
	v_mfma_f32_16x16x32_bf16 v[112:115], v[178:181], v[186:189], v[112:115]
	v_mfma_f32_16x16x32_bf16 v[100:103], v[170:173], v[196:199], v[100:103]
	v_mfma_f32_16x16x32_bf16 v[96:99], v[178:181], v[196:199], v[96:99]
	v_mfma_f32_16x16x32_bf16 v[84:87], v[170:173], v[204:207], v[84:87]
	v_mfma_f32_16x16x32_bf16 v[80:83], v[178:181], v[204:207], v[80:83]
	v_mfma_f32_16x16x32_bf16 v[68:71], v[170:173], v[212:215], v[68:71]
	v_mfma_f32_16x16x32_bf16 v[64:67], v[178:181], v[212:215], v[64:67]
	s_setprio 0
	s_barrier
	s_add_i32 s56, s44, s36
	v_lshl_add_u64 v[216:217], s[30:31], 0, v[132:133]
	s_mov_b32 m0, s56
	ds_read_b128 v[182:185], v149 offset:16384
	ds_read_b128 v[186:189], v149 offset:17408
	ds_read_b128 v[192:195], v149 offset:18432
	ds_read_b128 v[196:199], v149 offset:19456
	ds_read_b128 v[200:203], v149 offset:20480
	ds_read_b128 v[204:207], v149 offset:21504
	ds_read_b128 v[208:211], v149 offset:22528
	ds_read_b128 v[212:215], v149 offset:23552
	global_load_lds_dwordx4 v[216:217], off
	s_add_i32 m0, s56, 0x2000
	s_add_u32 s56, s30, 0x80000
	v_lshl_add_u64 v[218:219], s[30:31], 0, v[128:129]
	s_addc_u32 s57, s31, 0
	s_add_i32 s58, s91, s36
	global_load_lds_dwordx4 v[218:219], off
	s_mov_b32 m0, s58
	v_lshl_add_u64 v[222:223], s[34:35], 0, v[130:131]
	global_load_lds_dwordx4 v132, s[56:57]
	s_add_i32 m0, s58, 0x2000
	s_nop 0
	global_load_lds_dwordx4 v128, s[56:57]
	v_lshl_add_u64 v[220:221], s[34:35], 0, v[134:135]
	s_mov_b32 m0, s27
	s_nop 0
	global_load_lds_dwordx4 v[220:221], off
	s_mov_b32 m0, s38
	s_nop 0
	global_load_lds_dwordx4 v[222:223], off
	s_waitcnt vmcnt(8)
	s_waitcnt lgkmcnt(0)
	s_barrier
; #define PG8_STAGE(bufoff, gbase, voff) do { _Pragma("unroll") for (int _i = 0; _i < 2; ++_i) \
;         __builtin_amdgcn_global_load_lds((const unsigned*)((const char*)(gbase) + (voff)[_i]), (LAS unsigned*)(lds + (bufoff) + ldsw + _i * 8192), 16, 0, 0); } while (0)
; #define PG8_LDA(dst, b, h) do { _Pragma("unroll") for (int m = 0; m < 4; ++m) _Pragma("unroll") for (int k = 0; k < 2; ++k) dst[m][k] = *(const LAS bf16x8*)(lds + PG8_SA(b, h) + aoff + m * 2048 + k * 1024); } while (0)
; #define PG8_LDB(dst, b, h) do { _Pragma("unroll") for (int n = 0; n < 2; ++n) _Pragma("unroll") for (int k = 0; k < 2; ++k) dst[n][k] = *(const LAS bf16x8*)(lds + PG8_SB(b, h) + boff + n * 2048 + k * 1024); } while (0)
; #define PG8_WAIT_V(n) asm volatile("s_waitcnt vmcnt(" #n ")" ::: "memory")
; #define PG8_WAIT_L(n) asm volatile("s_waitcnt lgkmcnt(" #n ")" ::: "memory")
; #define PG8_BAR __builtin_amdgcn_s_barrier()
; #define PG8_SCHED __builtin_amdgcn_sched_barrier(0)
; template <class Epi, class Sched, bool F8 = false>
; __device__ __forceinline__ void gemm_phase(LAS unsigned char* lds, const Gemm g, const Sched& S, const Epi& E) {
;     ...
;             PG8_WAIT_V(8); PG8_WAIT_L(0); PG8_BAR; PG8_MMA(1, 0, At, B0); PG8_MMA(1, 1, At, B1); PG8_BAR; PG8_SCHED;
;             PG8_LDB(B0, 1, 0); PG8_LDB(B1, 1, 1); PG8_SCHED; PG8_LDA(At, 1, 0); PG8_STAGE(PG8_SA(0, 1), a2 + hstepA, voffA);
;             PG8_WAIT_V(8); PG8_WAIT_L(0); PG8_BAR; PG8_MMA(0, 0, At, B0); PG8_MMA(0, 1, At, B1); PG8_BAR; PG8_SCHED;
	s_setprio 1
	s_waitcnt lgkmcnt(0)
	v_mfma_f32_16x16x32_bf16 v[60:63], v[150:153], v[182:185], v[60:63]
	v_mfma_f32_16x16x32_bf16 v[56:59], v[158:161], v[182:185], v[56:59]
	v_mfma_f32_16x16x32_bf16 v[44:47], v[150:153], v[192:195], v[44:47]
	v_mfma_f32_16x16x32_bf16 v[40:43], v[158:161], v[192:195], v[40:43]
	v_mfma_f32_16x16x32_bf16 v[28:31], v[150:153], v[200:203], v[28:31]
	v_mfma_f32_16x16x32_bf16 v[24:27], v[158:161], v[200:203], v[24:27]
	v_mfma_f32_16x16x32_bf16 v[12:15], v[150:153], v[208:211], v[12:15]
	v_mfma_f32_16x16x32_bf16 v[8:11], v[158:161], v[208:211], v[8:11]
	v_mfma_f32_16x16x32_bf16 v[60:63], v[154:157], v[186:189], v[60:63]
	v_mfma_f32_16x16x32_bf16 v[56:59], v[162:165], v[186:189], v[56:59]
	v_mfma_f32_16x16x32_bf16 v[44:47], v[154:157], v[196:199], v[44:47]
	v_mfma_f32_16x16x32_bf16 v[40:43], v[162:165], v[196:199], v[40:43]
	v_mfma_f32_16x16x32_bf16 v[28:31], v[154:157], v[204:207], v[28:31]
	v_mfma_f32_16x16x32_bf16 v[24:27], v[162:165], v[204:207], v[24:27]
	v_mfma_f32_16x16x32_bf16 v[12:15], v[154:157], v[212:215], v[12:15]
	v_mfma_f32_16x16x32_bf16 v[8:11], v[162:165], v[212:215], v[8:11]
	s_setprio 0
	s_setprio 1
	v_mfma_f32_16x16x32_bf16 v[52:55], v[166:169], v[182:185], v[52:55]
	v_mfma_f32_16x16x32_bf16 v[48:51], v[174:177], v[182:185], v[48:51]
	v_mfma_f32_16x16x32_bf16 v[36:39], v[166:169], v[192:195], v[36:39]
	v_mfma_f32_16x16x32_bf16 v[32:35], v[174:177], v[192:195], v[32:35]
	v_mfma_f32_16x16x32_bf16 v[20:23], v[166:169], v[200:203], v[20:23]
	v_mfma_f32_16x16x32_bf16 v[16:19], v[174:177], v[200:203], v[16:19]
	v_mfma_f32_16x16x32_bf16 v[4:7], v[166:169], v[208:211], v[4:7]
	v_mfma_f32_16x16x32_bf16 v[0:3], v[174:177], v[208:211], v[0:3]
	v_mfma_f32_16x16x32_bf16 v[52:55], v[170:173], v[186:189], v[52:55]
	v_mfma_f32_16x16x32_bf16 v[48:51], v[178:181], v[186:189], v[48:51]
	v_mfma_f32_16x16x32_bf16 v[36:39], v[170:173], v[196:199], v[36:39]
	v_mfma_f32_16x16x32_bf16 v[32:35], v[178:181], v[196:199], v[32:35]
	v_mfma_f32_16x16x32_bf16 v[20:23], v[170:173], v[204:207], v[20:23]
	v_mfma_f32_16x16x32_bf16 v[16:19], v[178:181], v[204:207], v[16:19]
	v_mfma_f32_16x16x32_bf16 v[4:7], v[170:173], v[212:215], v[4:7]
	v_mfma_f32_16x16x32_bf16 v[0:3], v[178:181], v[212:215], v[0:3]
	s_setprio 0
	s_barrier
	s_add_i32 s56, 0, 0x18000
	s_add_i32 s57, 0, 0x1c000
	v_add_u32_e32 v162, s56, v145
	v_add_u32_e32 v178, s57, v145
	ds_read_b128 v[150:153], v162
	ds_read_b128 v[154:157], v162 offset:1024
	ds_read_b128 v[158:161], v162 offset:2048
	ds_read_b128 v[162:165], v162 offset:3072
	ds_read_b128 v[166:169], v178
	ds_read_b128 v[170:173], v178 offset:1024
	ds_read_b128 v[174:177], v178 offset:2048
	ds_read_b128 v[178:181], v178 offset:3072
	s_add_u32 s34, s34, 0x80000
	s_addc_u32 s35, s35, 0
	s_mov_b32 m0, s39
	ds_read_b128 v[182:185], v149 offset:32768
	ds_read_b128 v[186:189], v149 offset:33792
	ds_read_b128 v[192:195], v149 offset:34816
	ds_read_b128 v[196:199], v149 offset:35840
	ds_read_b128 v[200:203], v149 offset:36864
	ds_read_b128 v[204:207], v149 offset:37888
	ds_read_b128 v[208:211], v149 offset:38912
	ds_read_b128 v[212:215], v149 offset:39936
	global_load_lds_dwordx4 v134, s[34:35]
	s_mov_b32 m0, s40
	s_nop 0
	global_load_lds_dwordx4 v130, s[34:35]
	s_waitcnt vmcnt(8)
	s_waitcnt lgkmcnt(0)
	s_barrier
	s_setprio 1
	s_waitcnt lgkmcnt(0)
	v_mfma_f32_16x16x32_bf16 v[124:127], v[150:153], v[182:185], v[124:127]
	v_mfma_f32_16x16x32_bf16 v[120:123], v[158:161], v[182:185], v[120:123]
	v_mfma_f32_16x16x32_bf16 v[108:111], v[150:153], v[192:195], v[108:111]
	v_mfma_f32_16x16x32_bf16 v[104:107], v[158:161], v[192:195], v[104:107]
	v_mfma_f32_16x16x32_bf16 v[92:95], v[150:153], v[200:203], v[92:95]
	v_mfma_f32_16x16x32_bf16 v[88:91], v[158:161], v[200:203], v[88:91]
	v_mfma_f32_16x16x32_bf16 v[76:79], v[150:153], v[208:211], v[76:79]
	v_mfma_f32_16x16x32_bf16 v[72:75], v[158:161], v[208:211], v[72:75]
	v_mfma_f32_16x16x32_bf16 v[124:127], v[154:157], v[186:189], v[124:127]
	v_mfma_f32_16x16x32_bf16 v[120:123], v[162:165], v[186:189], v[120:123]
	v_mfma_f32_16x16x32_bf16 v[108:111], v[154:157], v[196:199], v[108:111]
	v_mfma_f32_16x16x32_bf16 v[104:107], v[162:165], v[196:199], v[104:107]
	v_mfma_f32_16x16x32_bf16 v[92:95], v[154:157], v[204:207], v[92:95]
	v_mfma_f32_16x16x32_bf16 v[88:91], v[162:165], v[204:207], v[88:91]
	v_mfma_f32_16x16x32_bf16 v[76:79], v[154:157], v[212:215], v[76:79]
	v_mfma_f32_16x16x32_bf16 v[72:75], v[162:165], v[212:215], v[72:75]
	s_setprio 0
	s_setprio 1
	v_mfma_f32_16x16x32_bf16 v[116:119], v[166:169], v[182:185], v[116:119]
	v_mfma_f32_16x16x32_bf16 v[112:115], v[174:177], v[182:185], v[112:115]
	v_mfma_f32_16x16x32_bf16 v[100:103], v[166:169], v[192:195], v[100:103]
	v_mfma_f32_16x16x32_bf16 v[96:99], v[174:177], v[192:195], v[96:99]
	v_mfma_f32_16x16x32_bf16 v[84:87], v[166:169], v[200:203], v[84:87]
	v_mfma_f32_16x16x32_bf16 v[80:83], v[174:177], v[200:203], v[80:83]
	v_mfma_f32_16x16x32_bf16 v[68:71], v[166:169], v[208:211], v[68:71]
	v_mfma_f32_16x16x32_bf16 v[64:67], v[174:177], v[208:211], v[64:67]
	v_mfma_f32_16x16x32_bf16 v[116:119], v[170:173], v[186:189], v[116:119]
	v_mfma_f32_16x16x32_bf16 v[112:115], v[178:181], v[186:189], v[112:115]
	v_mfma_f32_16x16x32_bf16 v[100:103], v[170:173], v[196:199], v[100:103]
	v_mfma_f32_16x16x32_bf16 v[96:99], v[178:181], v[196:199], v[96:99]
	v_mfma_f32_16x16x32_bf16 v[84:87], v[170:173], v[204:207], v[84:87]
	v_mfma_f32_16x16x32_bf16 v[80:83], v[178:181], v[204:207], v[80:83]
	v_mfma_f32_16x16x32_bf16 v[68:71], v[170:173], v[212:215], v[68:71]
	v_mfma_f32_16x16x32_bf16 v[64:67], v[178:181], v[212:215], v[64:67]
	s_setprio 0
	s_barrier
; #define PG8_STAGE(bufoff, gbase, voff) do { _Pragma("unroll") for (int _i = 0; _i < 2; ++_i) \
;         __builtin_amdgcn_global_load_lds((const unsigned*)((const char*)(gbase) + (voff)[_i]), (LAS unsigned*)(lds + (bufoff) + ldsw + _i * 8192), 16, 0, 0); } while (0)
; #define PG8_LDA(dst, b, h) do { _Pragma("unroll") for (int m = 0; m < 4; ++m) _Pragma("unroll") for (int k = 0; k < 2; ++k) dst[m][k] = *(const LAS bf16x8*)(lds + PG8_SA(b, h) + aoff + m * 2048 + k * 1024); } while (0)
; #define PG8_WAIT_V(n) asm volatile("s_waitcnt vmcnt(" #n ")" ::: "memory")
; #define PG8_WAIT_L(n) asm volatile("s_waitcnt lgkmcnt(" #n ")" ::: "memory")
; #define PG8_BAR __builtin_amdgcn_s_barrier()
; #define PG8_SCHED __builtin_amdgcn_sched_barrier(0)
; template <class Epi, class Sched, bool F8 = false>
; __device__ __forceinline__ void gemm_phase(LAS unsigned char* lds, const Gemm g, const Sched& S, const Epi& E) {
;     ...
;             PG8_LDA(At, 1, 1); PG8_STAGE(PG8_SB(1, 0), b3, voffB); PG8_STAGE(PG8_SB(1, 1), b3 + hstepB, voffB); PG8_STAGE(PG8_SA(1, 0), a3, voffA);
;             PG8_WAIT_V(8); PG8_WAIT_L(0); PG8_BAR; PG8_MMA(1, 0, At, B0); PG8_MMA(1, 1, At, B1); PG8_BAR; PG8_SCHED;
;         }
	s_add_i32 s34, s56, s36
	s_add_i32 m0, s34, 0xffffff80
	ds_read_b128 v[182:185], v149 offset:49152
	ds_read_b128 v[186:189], v149 offset:50176
	ds_read_b128 v[192:195], v149 offset:51200
	ds_read_b128 v[196:199], v149 offset:52224
	ds_read_b128 v[200:203], v149 offset:53248
	ds_read_b128 v[204:207], v149 offset:54272
	ds_read_b128 v[208:211], v149 offset:55296
	ds_read_b128 v[212:215], v149 offset:56320
	global_load_lds_dwordx4 v[216:217], off offset:128
	s_add_i32 m0, s34, 0x1f80
	s_add_u32 s30, s30, 0x80080
	s_addc_u32 s31, s31, 0
	s_add_i32 s34, s57, s36
	global_load_lds_dwordx4 v[218:219], off offset:128
	s_mov_b32 m0, s34
	s_nop 0
	global_load_lds_dwordx4 v132, s[30:31]
	s_add_i32 m0, s34, 0x2000
	s_nop 0
	global_load_lds_dwordx4 v128, s[30:31]
	s_add_i32 m0, s42, 0xffffff80
	s_nop 0
	global_load_lds_dwordx4 v[220:221], off offset:128
	s_add_i32 m0, s43, 0xffffff80
	s_nop 0
	global_load_lds_dwordx4 v[222:223], off offset:128
	s_waitcnt vmcnt(8)
	s_waitcnt lgkmcnt(0)
	s_barrier
	s_setprio 1
	s_waitcnt lgkmcnt(0)
	v_mfma_f32_16x16x32_bf16 v[60:63], v[150:153], v[182:185], v[60:63]
	v_mfma_f32_16x16x32_bf16 v[56:59], v[158:161], v[182:185], v[56:59]
	v_mfma_f32_16x16x32_bf16 v[44:47], v[150:153], v[192:195], v[44:47]
	v_mfma_f32_16x16x32_bf16 v[40:43], v[158:161], v[192:195], v[40:43]
	v_mfma_f32_16x16x32_bf16 v[28:31], v[150:153], v[200:203], v[28:31]
	v_mfma_f32_16x16x32_bf16 v[24:27], v[158:161], v[200:203], v[24:27]
	v_mfma_f32_16x16x32_bf16 v[12:15], v[150:153], v[208:211], v[12:15]
	v_mfma_f32_16x16x32_bf16 v[8:11], v[158:161], v[208:211], v[8:11]
	v_mfma_f32_16x16x32_bf16 v[60:63], v[154:157], v[186:189], v[60:63]
	v_mfma_f32_16x16x32_bf16 v[56:59], v[162:165], v[186:189], v[56:59]
	v_mfma_f32_16x16x32_bf16 v[44:47], v[154:157], v[196:199], v[44:47]
	v_mfma_f32_16x16x32_bf16 v[40:43], v[162:165], v[196:199], v[40:43]
	v_mfma_f32_16x16x32_bf16 v[28:31], v[154:157], v[204:207], v[28:31]
	v_mfma_f32_16x16x32_bf16 v[24:27], v[162:165], v[204:207], v[24:27]
	v_mfma_f32_16x16x32_bf16 v[12:15], v[154:157], v[212:215], v[12:15]
	v_mfma_f32_16x16x32_bf16 v[8:11], v[162:165], v[212:215], v[8:11]
	s_setprio 0
	s_setprio 1
	v_mfma_f32_16x16x32_bf16 v[52:55], v[166:169], v[182:185], v[52:55]
	v_mfma_f32_16x16x32_bf16 v[48:51], v[174:177], v[182:185], v[48:51]
	v_mfma_f32_16x16x32_bf16 v[36:39], v[166:169], v[192:195], v[36:39]
	v_mfma_f32_16x16x32_bf16 v[32:35], v[174:177], v[192:195], v[32:35]
	v_mfma_f32_16x16x32_bf16 v[20:23], v[166:169], v[200:203], v[20:23]
	v_mfma_f32_16x16x32_bf16 v[16:19], v[174:177], v[200:203], v[16:19]
	v_mfma_f32_16x16x32_bf16 v[4:7], v[166:169], v[208:211], v[4:7]
	v_mfma_f32_16x16x32_bf16 v[0:3], v[174:177], v[208:211], v[0:3]
	v_mfma_f32_16x16x32_bf16 v[52:55], v[170:173], v[186:189], v[52:55]
	v_mfma_f32_16x16x32_bf16 v[48:51], v[178:181], v[186:189], v[48:51]
	v_mfma_f32_16x16x32_bf16 v[36:39], v[170:173], v[196:199], v[36:39]
	v_mfma_f32_16x16x32_bf16 v[32:35], v[178:181], v[196:199], v[32:35]
	v_mfma_f32_16x16x32_bf16 v[20:23], v[170:173], v[204:207], v[20:23]
	v_mfma_f32_16x16x32_bf16 v[16:19], v[178:181], v[204:207], v[16:19]
	v_mfma_f32_16x16x32_bf16 v[4:7], v[170:173], v[212:215], v[4:7]
	v_mfma_f32_16x16x32_bf16 v[0:3], v[178:181], v[212:215], v[0:3]
	s_setprio 0
	s_add_i32 s53, s53, 2
	s_add_u32 s28, s28, 0x100
	s_addc_u32 s29, s29, 0
	s_add_u32 s50, s50, 0x100
	s_addc_u32 s51, s51, 0
	s_cmp_gt_u32 s53, 29
	s_barrier
	s_cbranch_scc0 .LBB0_954
	s_and_b64 vcc, exec, s[14:15]
	s_cbranch_vccz .LBB0_957
	s_barrier

; #define PG8_STAGE(bufoff, gbase, voff) do { _Pragma("unroll") for (int _i = 0; _i < 2; ++_i) \
;         __builtin_amdgcn_global_load_lds((const unsigned*)((const char*)(gbase) + (voff)[_i]), (LAS unsigned*)(lds + (bufoff) + ldsw + _i * 8192), 16, 0, 0); } while (0)
; #define PG8_LDA(dst, b, h) do { _Pragma("unroll") for (int m = 0; m < 4; ++m) _Pragma("unroll") for (int k = 0; k < 2; ++k) dst[m][k] = *(const LAS bf16x8*)(lds + PG8_SA(b, h) + aoff + m * 2048 + k * 1024); } while (0)
; #define PG8_LDB(dst, b, h) do { _Pragma("unroll") for (int n = 0; n < 2; ++n) _Pragma("unroll") for (int k = 0; k < 2; ++k) dst[n][k] = *(const LAS bf16x8*)(lds + PG8_SB(b, h) + boff + n * 2048 + k * 1024); } while (0)
; #define PG8_WAIT_V(n) asm volatile("s_waitcnt vmcnt(" #n ")" ::: "memory")
; #define PG8_WAIT_L(n) asm volatile("s_waitcnt lgkmcnt(" #n ")" ::: "memory")
; #define PG8_BAR __builtin_amdgcn_s_barrier()
; #define PG8_SCHED __builtin_amdgcn_sched_barrier(0)
; template <class Epi, class Sched, bool F8 = false>
; __device__ __forceinline__ void gemm_phase(LAS unsigned char* lds, const Gemm g, const Sched& S, const Epi& E) {
;     ...
;         for (int t = 0; t < nt; t += 2) {
;             const bool last = (t == nt - 2);
;             const char* a1 = cA + (size_t)(t + 1) * kstep;
;             const char* a2 = last ? nA : cA + (size_t)(t + 2) * kstep; const char* b2 = last ? nB : cB + (size_t)(t + 2) * kstep;
;             const char* a3 = a2 + kstep; const char* b3 = b2 + kstep;
;             PG8_LDB(B0, 0, 0); PG8_LDB(B1, 0, 1); PG8_SCHED; PG8_LDA(At, 0, 0); PG8_STAGE(PG8_SA(1, 1), a1 + hstepA, voffA);
;             PG8_WAIT_V(8); PG8_WAIT_L(0); PG8_BAR; PG8_MMA(0, 0, At, B0); PG8_MMA(0, 1, At, B1); PG8_BAR; PG8_SCHED;
;             PG8_LDA(At, 0, 1); PG8_STAGE(PG8_SB(0, 0), b2, voffB); PG8_STAGE(PG8_SB(0, 1), b2 + hstepB, voffB); PG8_STAGE(PG8_SA(0, 0), a2, voffA);
;             PG8_WAIT_V(8); PG8_WAIT_L(0); PG8_BAR; PG8_MMA(1, 0, At, B0); PG8_MMA(1, 1, At, B1); PG8_BAR; PG8_SCHED;
.LBB0_1030:
	ds_read_b128 v[144:147], v183
	ds_read_b128 v[148:151], v183 offset:1024
	ds_read_b128 v[152:155], v183 offset:2048
	ds_read_b128 v[156:159], v183 offset:3072
	ds_read_b128 v[160:163], v184
	ds_read_b128 v[164:167], v184 offset:1024
	ds_read_b128 v[168:171], v184 offset:2048
	ds_read_b128 v[172:175], v184 offset:3072
	s_add_u32 s28, s26, 0x100
	s_addc_u32 s29, s27, 0
	s_cmpk_eq_i32 s53, 0x54
	s_cselect_b32 s35, s9, s29
	s_cselect_b32 s34, s8, s28
	s_cselect_b32 s31, s25, s51
	s_cselect_b32 s30, s24, s50
	s_add_i32 m0, s37, 0xc000
	ds_read_b128 v[176:179], v185
	ds_read_b128 v[186:189], v185 offset:1024
	ds_read_b128 v[192:195], v185 offset:2048
	ds_read_b128 v[196:199], v185 offset:3072
	ds_read_b128 v[200:203], v185 offset:4096
	ds_read_b128 v[204:207], v185 offset:5120
	ds_read_b128 v[208:211], v185 offset:6144
	ds_read_b128 v[212:215], v185 offset:7168
	global_load_lds_dwordx4 v136, s[26:27]
	s_add_i32 m0, s37, 0xe000
	s_nop 0
	global_load_lds_dwordx4 v138, s[26:27]
	s_waitcnt vmcnt(8)
	s_waitcnt lgkmcnt(0)
	s_barrier
	s_setprio 1
	s_waitcnt lgkmcnt(0)
	v_mfma_f32_16x16x32_bf16 v[124:127], v[144:147], v[176:179], v[124:127]
	v_mfma_f32_16x16x32_bf16 v[120:123], v[152:155], v[176:179], v[120:123]
	v_mfma_f32_16x16x32_bf16 v[108:111], v[144:147], v[192:195], v[108:111]
	v_mfma_f32_16x16x32_bf16 v[104:107], v[152:155], v[192:195], v[104:107]
	v_mfma_f32_16x16x32_bf16 v[92:95], v[144:147], v[200:203], v[92:95]
	v_mfma_f32_16x16x32_bf16 v[88:91], v[152:155], v[200:203], v[88:91]
	v_mfma_f32_16x16x32_bf16 v[76:79], v[144:147], v[208:211], v[76:79]
	v_mfma_f32_16x16x32_bf16 v[72:75], v[152:155], v[208:211], v[72:75]
	v_mfma_f32_16x16x32_bf16 v[124:127], v[148:151], v[186:189], v[124:127]
	v_mfma_f32_16x16x32_bf16 v[120:123], v[156:159], v[186:189], v[120:123]
	v_mfma_f32_16x16x32_bf16 v[108:111], v[148:151], v[196:199], v[108:111]
	v_mfma_f32_16x16x32_bf16 v[104:107], v[156:159], v[196:199], v[104:107]
	v_mfma_f32_16x16x32_bf16 v[92:95], v[148:151], v[204:207], v[92:95]
	v_mfma_f32_16x16x32_bf16 v[88:91], v[156:159], v[204:207], v[88:91]
	v_mfma_f32_16x16x32_bf16 v[76:79], v[148:151], v[212:215], v[76:79]
	v_mfma_f32_16x16x32_bf16 v[72:75], v[156:159], v[212:215], v[72:75]
	s_setprio 0
	s_setprio 1
	v_mfma_f32_16x16x32_bf16 v[116:119], v[160:163], v[176:179], v[116:119]
	v_mfma_f32_16x16x32_bf16 v[112:115], v[168:171], v[176:179], v[112:115]
	v_mfma_f32_16x16x32_bf16 v[100:103], v[160:163], v[192:195], v[100:103]
	v_mfma_f32_16x16x32_bf16 v[96:99], v[168:171], v[192:195], v[96:99]
	v_mfma_f32_16x16x32_bf16 v[84:87], v[160:163], v[200:203], v[84:87]
	v_mfma_f32_16x16x32_bf16 v[80:83], v[168:171], v[200:203], v[80:83]
	v_mfma_f32_16x16x32_bf16 v[68:71], v[160:163], v[208:211], v[68:71]
	v_mfma_f32_16x16x32_bf16 v[64:67], v[168:171], v[208:211], v[64:67]
	v_mfma_f32_16x16x32_bf16 v[116:119], v[164:167], v[186:189], v[116:119]
	v_mfma_f32_16x16x32_bf16 v[112:115], v[172:175], v[186:189], v[112:115]
	v_mfma_f32_16x16x32_bf16 v[100:103], v[164:167], v[196:199], v[100:103]
	v_mfma_f32_16x16x32_bf16 v[96:99], v[172:175], v[196:199], v[96:99]
	v_mfma_f32_16x16x32_bf16 v[84:87], v[164:167], v[204:207], v[84:87]
	v_mfma_f32_16x16x32_bf16 v[80:83], v[172:175], v[204:207], v[80:83]
	v_mfma_f32_16x16x32_bf16 v[68:71], v[164:167], v[212:215], v[68:71]
	v_mfma_f32_16x16x32_bf16 v[64:67], v[172:175], v[212:215], v[64:67]
	s_setprio 0
	s_barrier
	s_add_i32 s26, s44, s23
	v_lshl_add_u64 v[216:217], s[30:31], 0, v[132:133]
	s_mov_b32 m0, s26
	ds_read_b128 v[176:179], v185 offset:16384
	ds_read_b128 v[186:189], v185 offset:17408
	ds_read_b128 v[192:195], v185 offset:18432
	ds_read_b128 v[196:199], v185 offset:19456
	ds_read_b128 v[200:203], v185 offset:20480
	ds_read_b128 v[204:207], v185 offset:21504
	ds_read_b128 v[208:211], v185 offset:22528
	ds_read_b128 v[212:215], v185 offset:23552
	global_load_lds_dwordx4 v[216:217], off
	s_add_i32 m0, s26, 0x2000
	s_add_u32 s26, s30, 0x160000
	v_lshl_add_u64 v[218:219], s[30:31], 0, v[128:129]
	s_addc_u32 s27, s31, 0
	s_add_i32 s56, s91, s23
	global_load_lds_dwordx4 v[218:219], off
	s_mov_b32 m0, s56
	v_lshl_add_u64 v[222:223], s[34:35], 0, v[130:131]
	global_load_lds_dwordx4 v132, s[26:27]
	s_add_i32 m0, s56, 0x2000
	s_nop 0
	global_load_lds_dwordx4 v128, s[26:27]
	v_lshl_add_u64 v[220:221], s[34:35], 0, v[134:135]
	s_mov_b32 m0, s37
	s_nop 0
	global_load_lds_dwordx4 v[220:221], off
	s_mov_b32 m0, s38
	s_nop 0
	global_load_lds_dwordx4 v[222:223], off
	s_waitcnt vmcnt(8)
	s_waitcnt lgkmcnt(0)
	s_barrier
; #define PG8_STAGE(bufoff, gbase, voff) do { _Pragma("unroll") for (int _i = 0; _i < 2; ++_i) \
;         __builtin_amdgcn_global_load_lds((const unsigned*)((const char*)(gbase) + (voff)[_i]), (LAS unsigned*)(lds + (bufoff) + ldsw + _i * 8192), 16, 0, 0); } while (0)
; #define PG8_LDA(dst, b, h) do { _Pragma("unroll") for (int m = 0; m < 4; ++m) _Pragma("unroll") for (int k = 0; k < 2; ++k) dst[m][k] = *(const LAS bf16x8*)(lds + PG8_SA(b, h) + aoff + m * 2048 + k * 1024); } while (0)
; #define PG8_LDB(dst, b, h) do { _Pragma("unroll") for (int n = 0; n < 2; ++n) _Pragma("unroll") for (int k = 0; k < 2; ++k) dst[n][k] = *(const LAS bf16x8*)(lds + PG8_SB(b, h) + boff + n * 2048 + k * 1024); } while (0)
; #define PG8_WAIT_V(n) asm volatile("s_waitcnt vmcnt(" #n ")" ::: "memory")
; #define PG8_WAIT_L(n) asm volatile("s_waitcnt lgkmcnt(" #n ")" ::: "memory")
; #define PG8_BAR __builtin_amdgcn_s_barrier()
; #define PG8_SCHED __builtin_amdgcn_sched_barrier(0)
; template <class Epi, class Sched, bool F8 = false>
; __device__ __forceinline__ void gemm_phase(LAS unsigned char* lds, const Gemm g, const Sched& S, const Epi& E) {
;     ...
;             PG8_WAIT_V(8); PG8_WAIT_L(0); PG8_BAR; PG8_MMA(1, 0, At, B0); PG8_MMA(1, 1, At, B1); PG8_BAR; PG8_SCHED;
;             PG8_LDB(B0, 1, 0); PG8_LDB(B1, 1, 1); PG8_SCHED; PG8_LDA(At, 1, 0); PG8_STAGE(PG8_SA(0, 1), a2 + hstepA, voffA);
;             PG8_WAIT_V(8); PG8_WAIT_L(0); PG8_BAR; PG8_MMA(0, 0, At, B0); PG8_MMA(0, 1, At, B1); PG8_BAR; PG8_SCHED;
	s_setprio 1
	s_waitcnt lgkmcnt(0)
	v_mfma_f32_16x16x32_bf16 v[60:63], v[144:147], v[176:179], v[60:63]
	v_mfma_f32_16x16x32_bf16 v[56:59], v[152:155], v[176:179], v[56:59]
	v_mfma_f32_16x16x32_bf16 v[44:47], v[144:147], v[192:195], v[44:47]
	v_mfma_f32_16x16x32_bf16 v[40:43], v[152:155], v[192:195], v[40:43]
	v_mfma_f32_16x16x32_bf16 v[28:31], v[144:147], v[200:203], v[28:31]
	v_mfma_f32_16x16x32_bf16 v[24:27], v[152:155], v[200:203], v[24:27]
	v_mfma_f32_16x16x32_bf16 v[12:15], v[144:147], v[208:211], v[12:15]
	v_mfma_f32_16x16x32_bf16 v[8:11], v[152:155], v[208:211], v[8:11]
	v_mfma_f32_16x16x32_bf16 v[60:63], v[148:151], v[186:189], v[60:63]
	v_mfma_f32_16x16x32_bf16 v[56:59], v[156:159], v[186:189], v[56:59]
	v_mfma_f32_16x16x32_bf16 v[44:47], v[148:151], v[196:199], v[44:47]
	v_mfma_f32_16x16x32_bf16 v[40:43], v[156:159], v[196:199], v[40:43]
	v_mfma_f32_16x16x32_bf16 v[28:31], v[148:151], v[204:207], v[28:31]
	v_mfma_f32_16x16x32_bf16 v[24:27], v[156:159], v[204:207], v[24:27]
	v_mfma_f32_16x16x32_bf16 v[12:15], v[148:151], v[212:215], v[12:15]
	v_mfma_f32_16x16x32_bf16 v[8:11], v[156:159], v[212:215], v[8:11]
	s_setprio 0
	s_setprio 1
	v_mfma_f32_16x16x32_bf16 v[52:55], v[160:163], v[176:179], v[52:55]
	v_mfma_f32_16x16x32_bf16 v[48:51], v[168:171], v[176:179], v[48:51]
	v_mfma_f32_16x16x32_bf16 v[36:39], v[160:163], v[192:195], v[36:39]
	v_mfma_f32_16x16x32_bf16 v[32:35], v[168:171], v[192:195], v[32:35]
	v_mfma_f32_16x16x32_bf16 v[20:23], v[160:163], v[200:203], v[20:23]
	v_mfma_f32_16x16x32_bf16 v[16:19], v[168:171], v[200:203], v[16:19]
	v_mfma_f32_16x16x32_bf16 v[4:7], v[160:163], v[208:211], v[4:7]
	v_mfma_f32_16x16x32_bf16 v[0:3], v[168:171], v[208:211], v[0:3]
	v_mfma_f32_16x16x32_bf16 v[52:55], v[164:167], v[186:189], v[52:55]
	v_mfma_f32_16x16x32_bf16 v[48:51], v[172:175], v[186:189], v[48:51]
	v_mfma_f32_16x16x32_bf16 v[36:39], v[164:167], v[196:199], v[36:39]
	v_mfma_f32_16x16x32_bf16 v[32:35], v[172:175], v[196:199], v[32:35]
	v_mfma_f32_16x16x32_bf16 v[20:23], v[164:167], v[204:207], v[20:23]
	v_mfma_f32_16x16x32_bf16 v[16:19], v[172:175], v[204:207], v[16:19]
	v_mfma_f32_16x16x32_bf16 v[4:7], v[164:167], v[212:215], v[4:7]
	v_mfma_f32_16x16x32_bf16 v[0:3], v[172:175], v[212:215], v[0:3]
	s_setprio 0
	s_barrier
	s_add_i32 s56, 0, 0x18000
	s_add_i32 s57, 0, 0x1c000
	v_add_u32_e32 v156, s56, v181
	v_add_u32_e32 v172, s57, v181
	ds_read_b128 v[144:147], v156
	ds_read_b128 v[148:151], v156 offset:1024
	ds_read_b128 v[152:155], v156 offset:2048
	ds_read_b128 v[156:159], v156 offset:3072
	ds_read_b128 v[160:163], v172
	ds_read_b128 v[164:167], v172 offset:1024
	ds_read_b128 v[168:171], v172 offset:2048
	ds_read_b128 v[172:175], v172 offset:3072
	s_add_u32 s26, s34, 0x160000
	s_addc_u32 s27, s35, 0
	s_mov_b32 m0, s39
	ds_read_b128 v[176:179], v185 offset:32768
	ds_read_b128 v[186:189], v185 offset:33792
	ds_read_b128 v[192:195], v185 offset:34816
	ds_read_b128 v[196:199], v185 offset:35840
	ds_read_b128 v[200:203], v185 offset:36864
	ds_read_b128 v[204:207], v185 offset:37888
	ds_read_b128 v[208:211], v185 offset:38912
	ds_read_b128 v[212:215], v185 offset:39936
	global_load_lds_dwordx4 v134, s[26:27]
	s_mov_b32 m0, s40
	s_nop 0
	global_load_lds_dwordx4 v130, s[26:27]
	s_waitcnt vmcnt(8)
	s_waitcnt lgkmcnt(0)
	s_barrier
	s_setprio 1
	s_waitcnt lgkmcnt(0)
	v_mfma_f32_16x16x32_bf16 v[124:127], v[144:147], v[176:179], v[124:127]
	v_mfma_f32_16x16x32_bf16 v[120:123], v[152:155], v[176:179], v[120:123]
	v_mfma_f32_16x16x32_bf16 v[108:111], v[144:147], v[192:195], v[108:111]
	v_mfma_f32_16x16x32_bf16 v[104:107], v[152:155], v[192:195], v[104:107]
	v_mfma_f32_16x16x32_bf16 v[92:95], v[144:147], v[200:203], v[92:95]
	v_mfma_f32_16x16x32_bf16 v[88:91], v[152:155], v[200:203], v[88:91]
	v_mfma_f32_16x16x32_bf16 v[76:79], v[144:147], v[208:211], v[76:79]
	v_mfma_f32_16x16x32_bf16 v[72:75], v[152:155], v[208:211], v[72:75]
	v_mfma_f32_16x16x32_bf16 v[124:127], v[148:151], v[186:189], v[124:127]
	v_mfma_f32_16x16x32_bf16 v[120:123], v[156:159], v[186:189], v[120:123]
	v_mfma_f32_16x16x32_bf16 v[108:111], v[148:151], v[196:199], v[108:111]
	v_mfma_f32_16x16x32_bf16 v[104:107], v[156:159], v[196:199], v[104:107]
	v_mfma_f32_16x16x32_bf16 v[92:95], v[148:151], v[204:207], v[92:95]
	v_mfma_f32_16x16x32_bf16 v[88:91], v[156:159], v[204:207], v[88:91]
	v_mfma_f32_16x16x32_bf16 v[76:79], v[148:151], v[212:215], v[76:79]
	v_mfma_f32_16x16x32_bf16 v[72:75], v[156:159], v[212:215], v[72:75]
	s_setprio 0
	s_setprio 1
	v_mfma_f32_16x16x32_bf16 v[116:119], v[160:163], v[176:179], v[116:119]
	v_mfma_f32_16x16x32_bf16 v[112:115], v[168:171], v[176:179], v[112:115]
	v_mfma_f32_16x16x32_bf16 v[100:103], v[160:163], v[192:195], v[100:103]
	v_mfma_f32_16x16x32_bf16 v[96:99], v[168:171], v[192:195], v[96:99]
	v_mfma_f32_16x16x32_bf16 v[84:87], v[160:163], v[200:203], v[84:87]
	v_mfma_f32_16x16x32_bf16 v[80:83], v[168:171], v[200:203], v[80:83]
	v_mfma_f32_16x16x32_bf16 v[68:71], v[160:163], v[208:211], v[68:71]
	v_mfma_f32_16x16x32_bf16 v[64:67], v[168:171], v[208:211], v[64:67]
	v_mfma_f32_16x16x32_bf16 v[116:119], v[164:167], v[186:189], v[116:119]
	v_mfma_f32_16x16x32_bf16 v[112:115], v[172:175], v[186:189], v[112:115]
	v_mfma_f32_16x16x32_bf16 v[100:103], v[164:167], v[196:199], v[100:103]
	v_mfma_f32_16x16x32_bf16 v[96:99], v[172:175], v[196:199], v[96:99]
	v_mfma_f32_16x16x32_bf16 v[84:87], v[164:167], v[204:207], v[84:87]
	v_mfma_f32_16x16x32_bf16 v[80:83], v[172:175], v[204:207], v[80:83]
	v_mfma_f32_16x16x32_bf16 v[68:71], v[164:167], v[212:215], v[68:71]
	v_mfma_f32_16x16x32_bf16 v[64:67], v[172:175], v[212:215], v[64:67]
	s_setprio 0
	s_barrier
; #define PG8_STAGE(bufoff, gbase, voff) do { _Pragma("unroll") for (int _i = 0; _i < 2; ++_i) \
;         __builtin_amdgcn_global_load_lds((const unsigned*)((const char*)(gbase) + (voff)[_i]), (LAS unsigned*)(lds + (bufoff) + ldsw + _i * 8192), 16, 0, 0); } while (0)
; #define PG8_LDA(dst, b, h) do { _Pragma("unroll") for (int m = 0; m < 4; ++m) _Pragma("unroll") for (int k = 0; k < 2; ++k) dst[m][k] = *(const LAS bf16x8*)(lds + PG8_SA(b, h) + aoff + m * 2048 + k * 1024); } while (0)
; #define PG8_WAIT_V(n) asm volatile("s_waitcnt vmcnt(" #n ")" ::: "memory")
; #define PG8_WAIT_L(n) asm volatile("s_waitcnt lgkmcnt(" #n ")" ::: "memory")
; #define PG8_BAR __builtin_amdgcn_s_barrier()
; #define PG8_SCHED __builtin_amdgcn_sched_barrier(0)
; template <class Epi, class Sched, bool F8 = false>
; __device__ __forceinline__ void gemm_phase(LAS unsigned char* lds, const Gemm g, const Sched& S, const Epi& E) {
;     ...
;             PG8_LDA(At, 1, 1); PG8_STAGE(PG8_SB(1, 0), b3, voffB); PG8_STAGE(PG8_SB(1, 1), b3 + hstepB, voffB); PG8_STAGE(PG8_SA(1, 0), a3, voffA);
;             PG8_WAIT_V(8); PG8_WAIT_L(0); PG8_BAR; PG8_MMA(1, 0, At, B0); PG8_MMA(1, 1, At, B1); PG8_BAR; PG8_SCHED;
;         }
	s_add_i32 s26, s56, s23
	s_add_i32 m0, s26, 0xffffff80
	ds_read_b128 v[176:179], v185 offset:49152
	ds_read_b128 v[186:189], v185 offset:50176
	ds_read_b128 v[192:195], v185 offset:51200
	ds_read_b128 v[196:199], v185 offset:52224
	ds_read_b128 v[200:203], v185 offset:53248
	ds_read_b128 v[204:207], v185 offset:54272
	ds_read_b128 v[208:211], v185 offset:55296
	ds_read_b128 v[212:215], v185 offset:56320
	global_load_lds_dwordx4 v[216:217], off offset:128
	s_add_i32 m0, s26, 0x1f80
	s_add_u32 s26, s30, 0x160080
	s_addc_u32 s27, s31, 0
	s_add_i32 s30, s57, s23
	global_load_lds_dwordx4 v[218:219], off offset:128
	s_mov_b32 m0, s30
	s_nop 0
	global_load_lds_dwordx4 v132, s[26:27]
	s_add_i32 m0, s30, 0x2000
	s_nop 0
	global_load_lds_dwordx4 v128, s[26:27]
	s_add_i32 m0, s42, 0xffffff80
	s_nop 0
	global_load_lds_dwordx4 v[220:221], off offset:128
	s_add_i32 m0, s43, 0xffffff80
	s_nop 0
	global_load_lds_dwordx4 v[222:223], off offset:128
	s_waitcnt vmcnt(8)
	s_waitcnt lgkmcnt(0)
	s_barrier
	s_setprio 1
	s_waitcnt lgkmcnt(0)
	v_mfma_f32_16x16x32_bf16 v[60:63], v[144:147], v[176:179], v[60:63]
	v_mfma_f32_16x16x32_bf16 v[56:59], v[152:155], v[176:179], v[56:59]
	v_mfma_f32_16x16x32_bf16 v[44:47], v[144:147], v[192:195], v[44:47]
	v_mfma_f32_16x16x32_bf16 v[40:43], v[152:155], v[192:195], v[40:43]
	v_mfma_f32_16x16x32_bf16 v[28:31], v[144:147], v[200:203], v[28:31]
	v_mfma_f32_16x16x32_bf16 v[24:27], v[152:155], v[200:203], v[24:27]
	v_mfma_f32_16x16x32_bf16 v[12:15], v[144:147], v[208:211], v[12:15]
	v_mfma_f32_16x16x32_bf16 v[8:11], v[152:155], v[208:211], v[8:11]
	v_mfma_f32_16x16x32_bf16 v[60:63], v[148:151], v[186:189], v[60:63]
	v_mfma_f32_16x16x32_bf16 v[56:59], v[156:159], v[186:189], v[56:59]
	v_mfma_f32_16x16x32_bf16 v[44:47], v[148:151], v[196:199], v[44:47]
	v_mfma_f32_16x16x32_bf16 v[40:43], v[156:159], v[196:199], v[40:43]
	v_mfma_f32_16x16x32_bf16 v[28:31], v[148:151], v[204:207], v[28:31]
	v_mfma_f32_16x16x32_bf16 v[24:27], v[156:159], v[204:207], v[24:27]
	v_mfma_f32_16x16x32_bf16 v[12:15], v[148:151], v[212:215], v[12:15]
	v_mfma_f32_16x16x32_bf16 v[8:11], v[156:159], v[212:215], v[8:11]
	s_setprio 0
	s_setprio 1
	v_mfma_f32_16x16x32_bf16 v[52:55], v[160:163], v[176:179], v[52:55]
	v_mfma_f32_16x16x32_bf16 v[48:51], v[168:171], v[176:179], v[48:51]
	v_mfma_f32_16x16x32_bf16 v[36:39], v[160:163], v[192:195], v[36:39]
	v_mfma_f32_16x16x32_bf16 v[32:35], v[168:171], v[192:195], v[32:35]
	v_mfma_f32_16x16x32_bf16 v[20:23], v[160:163], v[200:203], v[20:23]
	v_mfma_f32_16x16x32_bf16 v[16:19], v[168:171], v[200:203], v[16:19]
	v_mfma_f32_16x16x32_bf16 v[4:7], v[160:163], v[208:211], v[4:7]
	v_mfma_f32_16x16x32_bf16 v[0:3], v[168:171], v[208:211], v[0:3]
	v_mfma_f32_16x16x32_bf16 v[52:55], v[164:167], v[186:189], v[52:55]
	v_mfma_f32_16x16x32_bf16 v[48:51], v[172:175], v[186:189], v[48:51]
	v_mfma_f32_16x16x32_bf16 v[36:39], v[164:167], v[196:199], v[36:39]
	v_mfma_f32_16x16x32_bf16 v[32:35], v[172:175], v[196:199], v[32:35]
	v_mfma_f32_16x16x32_bf16 v[20:23], v[164:167], v[204:207], v[20:23]
	v_mfma_f32_16x16x32_bf16 v[16:19], v[172:175], v[204:207], v[16:19]
	v_mfma_f32_16x16x32_bf16 v[4:7], v[164:167], v[212:215], v[4:7]
	v_mfma_f32_16x16x32_bf16 v[0:3], v[172:175], v[212:215], v[0:3]
	s_setprio 0
	s_add_i32 s53, s53, 2
	s_add_u32 s50, s50, 0x100
	s_addc_u32 s51, s51, 0
	s_cmpk_gt_u32 s53, 0x55
	s_mov_b64 s[26:27], s[28:29]
	s_barrier
	s_cbranch_scc0 .LBB0_1030
	s_and_b64 vcc, exec, s[20:21]
	s_cbranch_vccz .LBB0_1033
	s_barrier
